# both MFMAs of each accumulator issued back to back (k0 then k1 chained) in all GEMM loops, on top of 8-byte aligned MFMA runs
# speedup vs baseline: 1.0074x; 1.0047x over previous
; #define PG8_STAGE(bufoff, gbase, voff) do { _Pragma("unroll") for (int _i = 0; _i < 2; ++_i) \
;         __builtin_amdgcn_global_load_lds((const unsigned*)((const char*)(gbase) + (voff)[_i]), (LAS unsigned*)(lds + (bufoff) + ldsw + _i * 8192), 16, 0, 0); } while (0)
; #define PG8_LDA(dst, b, h) do { _Pragma("unroll") for (int m = 0; m < 4; ++m) _Pragma("unroll") for (int k = 0; k < 2; ++k) dst[m][k] = *(const LAS bf16x8*)(lds + PG8_SA(b, h) + aoff + m * 2048 + k * 1024); } while (0)
; #define PG8_LDB(dst, b, h) do { _Pragma("unroll") for (int n = 0; n < 2; ++n) _Pragma("unroll") for (int k = 0; k < 2; ++k) dst[n][k] = *(const LAS bf16x8*)(lds + PG8_SB(b, h) + boff + n * 2048 + k * 1024); } while (0)
; #define PG8_MMA(ai, bj, At, Bt) do { __builtin_amdgcn_s_setprio(1); _Pragma("unroll") for (int m = 0; m < 4; ++m) _Pragma("unroll") for (int n = 0; n < 2; ++n) _Pragma("unroll") for (int k = 0; k < 2; ++k) \
;         acc[ai][bj][m][n] = __builtin_amdgcn_mfma_f32_16x16x32_bf16(Bt[n][k], At[m][k], acc[ai][bj][m][n], 0, 0, 0); __builtin_amdgcn_s_setprio(0); } while (0)
; #define PG8_WAIT_V(n) asm volatile("s_waitcnt vmcnt(" #n ")" ::: "memory")
; #define PG8_WAIT_L(n) asm volatile("s_waitcnt lgkmcnt(" #n ")" ::: "memory")
; #define PG8_BAR __builtin_amdgcn_s_barrier()
; #define PG8_SCHED __builtin_amdgcn_sched_barrier(0)
; template <int FIXED_NT  , class Epi, class Sched>
; __device__ __forceinline__ void gemm_phase(LAS unsigned char* lds, const int tid_in, const int lda, const int ldb, const Sched& S, const Epi& E) {
;     ...
;         for (int t = 0; t < nt; t += 2) {
;             const bool last = (t == nt - 2);
;             const char* a1 = cA + (size_t)(t + 1) * kstep;
;             const char* a2 = last ? nA : cA + (size_t)(t + 2) * kstep; const char* b2 = last ? nB : cB + (size_t)(t + 2) * kstep;
;             const char* a3 = a2 + kstep; const char* b3 = b2 + kstep;
;             PG8_LDB(B0, 0, 0); PG8_LDB(B1, 0, 1); PG8_SCHED; PG8_LDA(At, 0, 0); PG8_STAGE(PG8_SA(1, 1), a1 + hstepA, voffA);
;             PG8_WAIT_V(8); PG8_WAIT_L(0); PG8_BAR; PG8_MMA(0, 0, At, B0); PG8_MMA(0, 1, At, B1); PG8_BAR; PG8_SCHED;
;             PG8_LDA(At, 0, 1); PG8_STAGE(PG8_SB(0, 0), b2, voffB); PG8_STAGE(PG8_SB(0, 1), b2 + hstepB, voffB); PG8_STAGE(PG8_SA(0, 0), a2, voffA);
.LBB0_244:
	s_waitcnt lgkmcnt(0)
	ds_read_b128 v[128:131], v183
	ds_read_b128 v[132:135], v183 offset:1024
	ds_read_b128 v[136:139], v183 offset:2048
	ds_read_b128 v[140:143], v183 offset:3072
	ds_read_b128 v[162:165], v184
	ds_read_b128 v[188:191], v184 offset:1024
	ds_read_b128 v[192:195], v184 offset:2048
	ds_read_b128 v[196:199], v184 offset:3072
	s_add_i32 s79, s57, 2
	s_add_u32 s24, s6, 0xfff80080
	s_addc_u32 s25, s7, -1
	s_cmp_eq_u32 s87, s57
	s_cselect_b32 s65, s59, s25
	s_cselect_b32 s64, s58, s24
	s_cselect_b32 s63, s61, s53
	s_cselect_b32 s62, s60, s14
	v_lshl_add_u64 v[166:167], s[6:7], 0, v[158:159]
	s_add_i32 m0, s67, 0xc000
	ds_read_b128 v[200:203], v185
	ds_read_b128 v[204:207], v185 offset:1024
	ds_read_b128 v[208:211], v185 offset:2048
	ds_read_b128 v[212:215], v185 offset:3072
	ds_read_b128 v[216:219], v185 offset:4096
	ds_read_b128 v[220:223], v185 offset:5120
	ds_read_b128 v[226:229], v185 offset:6144
	ds_read_b128 v[230:233], v185 offset:7168
	global_load_lds_dwordx4 v[166:167], off
	v_lshl_add_u64 v[166:167], s[6:7], 0, v[160:161]
	s_add_i32 m0, s67, 0xe000
	s_nop 0
	global_load_lds_dwordx4 v[166:167], off
	s_waitcnt vmcnt(8)
	s_waitcnt lgkmcnt(0)
	s_barrier
	s_setprio 1
	s_waitcnt lgkmcnt(0)
	v_mfma_f32_16x16x32_bf16 v[124:127], v[128:131], v[200:203], v[124:127]
	v_mfma_f32_16x16x32_bf16 v[124:127], v[132:135], v[204:207], v[124:127]
	v_mfma_f32_16x16x32_bf16 v[120:123], v[136:139], v[200:203], v[120:123]
	v_mfma_f32_16x16x32_bf16 v[120:123], v[140:143], v[204:207], v[120:123]
	v_mfma_f32_16x16x32_bf16 v[108:111], v[128:131], v[208:211], v[108:111]
	v_mfma_f32_16x16x32_bf16 v[108:111], v[132:135], v[212:215], v[108:111]
	v_mfma_f32_16x16x32_bf16 v[104:107], v[136:139], v[208:211], v[104:107]
	v_mfma_f32_16x16x32_bf16 v[104:107], v[140:143], v[212:215], v[104:107]
	v_mfma_f32_16x16x32_bf16 v[92:95], v[128:131], v[216:219], v[92:95]
	v_mfma_f32_16x16x32_bf16 v[92:95], v[132:135], v[220:223], v[92:95]
	v_mfma_f32_16x16x32_bf16 v[88:91], v[136:139], v[216:219], v[88:91]
	v_mfma_f32_16x16x32_bf16 v[88:91], v[140:143], v[220:223], v[88:91]
	v_mfma_f32_16x16x32_bf16 v[76:79], v[128:131], v[226:229], v[76:79]
	v_mfma_f32_16x16x32_bf16 v[76:79], v[132:135], v[230:233], v[76:79]
	v_mfma_f32_16x16x32_bf16 v[72:75], v[136:139], v[226:229], v[72:75]
	v_mfma_f32_16x16x32_bf16 v[72:75], v[140:143], v[230:233], v[72:75]
	s_setprio 0
	s_setprio 1
	v_mfma_f32_16x16x32_bf16 v[116:119], v[162:165], v[200:203], v[116:119]
	v_mfma_f32_16x16x32_bf16 v[116:119], v[188:191], v[204:207], v[116:119]
	v_mfma_f32_16x16x32_bf16 v[112:115], v[192:195], v[200:203], v[112:115]
	v_mfma_f32_16x16x32_bf16 v[112:115], v[196:199], v[204:207], v[112:115]
	v_mfma_f32_16x16x32_bf16 v[100:103], v[162:165], v[208:211], v[100:103]
	v_mfma_f32_16x16x32_bf16 v[100:103], v[188:191], v[212:215], v[100:103]
	v_mfma_f32_16x16x32_bf16 v[96:99], v[192:195], v[208:211], v[96:99]
	v_mfma_f32_16x16x32_bf16 v[96:99], v[196:199], v[212:215], v[96:99]
	v_mfma_f32_16x16x32_bf16 v[84:87], v[162:165], v[216:219], v[84:87]
	v_mfma_f32_16x16x32_bf16 v[84:87], v[188:191], v[220:223], v[84:87]
	v_mfma_f32_16x16x32_bf16 v[80:83], v[192:195], v[216:219], v[80:83]
	v_mfma_f32_16x16x32_bf16 v[80:83], v[196:199], v[220:223], v[80:83]
	v_mfma_f32_16x16x32_bf16 v[68:71], v[162:165], v[226:229], v[68:71]
	v_mfma_f32_16x16x32_bf16 v[68:71], v[188:191], v[230:233], v[68:71]
	v_mfma_f32_16x16x32_bf16 v[64:67], v[192:195], v[226:229], v[64:67]
	v_mfma_f32_16x16x32_bf16 v[64:67], v[196:199], v[230:233], v[64:67]
	s_setprio 0
	s_barrier
	s_add_i32 s24, s92, s66
	v_lshl_add_u64 v[166:167], s[62:63], 0, v[146:147]
	s_mov_b32 m0, s24
	ds_read_b128 v[200:203], v185 offset:16384
	ds_read_b128 v[204:207], v185 offset:17408
	ds_read_b128 v[208:211], v185 offset:18432
	ds_read_b128 v[212:215], v185 offset:19456
	ds_read_b128 v[216:219], v185 offset:20480
	ds_read_b128 v[220:223], v185 offset:21504
	ds_read_b128 v[226:229], v185 offset:22528
	ds_read_b128 v[230:233], v185 offset:23552
	global_load_lds_dwordx4 v[166:167], off
	s_add_i32 m0, s24, 0x2000
	s_add_u32 vcc_lo, s62, 0x80000
	v_lshl_add_u64 v[234:235], s[62:63], 0, v[150:151]
	s_addc_u32 vcc_hi, s63, 0
	s_add_i32 s24, s93, s66
	global_load_lds_dwordx4 v[234:235], off
	v_lshl_add_u64 v[236:237], vcc, 0, v[146:147]
	s_mov_b32 m0, s24
	v_lshl_add_u64 v[238:239], s[64:65], 0, v[148:149]
	global_load_lds_dwordx4 v[236:237], off
	v_lshl_add_u64 v[236:237], vcc, 0, v[150:151]
	s_add_i32 m0, s24, 0x2000
	s_nop 0
	global_load_lds_dwordx4 v[236:237], off
	v_lshl_add_u64 v[236:237], s[64:65], 0, v[144:145]
	s_mov_b32 m0, s67
	s_nop 0
	global_load_lds_dwordx4 v[236:237], off
	s_mov_b32 m0, s68
	s_nop 0
	global_load_lds_dwordx4 v[238:239], off
	s_nop 0
	s_waitcnt vmcnt(8)
	s_waitcnt lgkmcnt(0)
	s_barrier
; #define PG8_STAGE(bufoff, gbase, voff) do { _Pragma("unroll") for (int _i = 0; _i < 2; ++_i) \
;         __builtin_amdgcn_global_load_lds((const unsigned*)((const char*)(gbase) + (voff)[_i]), (LAS unsigned*)(lds + (bufoff) + ldsw + _i * 8192), 16, 0, 0); } while (0)
; #define PG8_LDA(dst, b, h) do { _Pragma("unroll") for (int m = 0; m < 4; ++m) _Pragma("unroll") for (int k = 0; k < 2; ++k) dst[m][k] = *(const LAS bf16x8*)(lds + PG8_SA(b, h) + aoff + m * 2048 + k * 1024); } while (0)
; #define PG8_LDB(dst, b, h) do { _Pragma("unroll") for (int n = 0; n < 2; ++n) _Pragma("unroll") for (int k = 0; k < 2; ++k) dst[n][k] = *(const LAS bf16x8*)(lds + PG8_SB(b, h) + boff + n * 2048 + k * 1024); } while (0)
; #define PG8_MMA(ai, bj, At, Bt) do { __builtin_amdgcn_s_setprio(1); _Pragma("unroll") for (int m = 0; m < 4; ++m) _Pragma("unroll") for (int n = 0; n < 2; ++n) _Pragma("unroll") for (int k = 0; k < 2; ++k) \
;         acc[ai][bj][m][n] = __builtin_amdgcn_mfma_f32_16x16x32_bf16(Bt[n][k], At[m][k], acc[ai][bj][m][n], 0, 0, 0); __builtin_amdgcn_s_setprio(0); } while (0)
; #define PG8_WAIT_V(n) asm volatile("s_waitcnt vmcnt(" #n ")" ::: "memory")
; #define PG8_WAIT_L(n) asm volatile("s_waitcnt lgkmcnt(" #n ")" ::: "memory")
; #define PG8_BAR __builtin_amdgcn_s_barrier()
; #define PG8_SCHED __builtin_amdgcn_sched_barrier(0)
; template <int FIXED_NT  , class Epi, class Sched>
; __device__ __forceinline__ void gemm_phase(LAS unsigned char* lds, const int tid_in, const int lda, const int ldb, const Sched& S, const Epi& E) {
;     ...
;             PG8_WAIT_V(8); PG8_WAIT_L(0); PG8_BAR; PG8_MMA(1, 0, At, B0); PG8_MMA(1, 1, At, B1); PG8_BAR; PG8_SCHED;
;             PG8_LDB(B0, 1, 0); PG8_LDB(B1, 1, 1); PG8_SCHED; PG8_LDA(At, 1, 0); PG8_STAGE(PG8_SA(0, 1), a2 + hstepA, voffA);
;             PG8_WAIT_V(8); PG8_WAIT_L(0); PG8_BAR; PG8_MMA(0, 0, At, B0); PG8_MMA(0, 1, At, B1); PG8_BAR; PG8_SCHED;
	s_setprio 1
	s_waitcnt lgkmcnt(0)
	v_mfma_f32_16x16x32_bf16 v[60:63], v[128:131], v[200:203], v[60:63]
	v_mfma_f32_16x16x32_bf16 v[60:63], v[132:135], v[204:207], v[60:63]
	v_mfma_f32_16x16x32_bf16 v[56:59], v[136:139], v[200:203], v[56:59]
	v_mfma_f32_16x16x32_bf16 v[56:59], v[140:143], v[204:207], v[56:59]
	v_mfma_f32_16x16x32_bf16 v[44:47], v[128:131], v[208:211], v[44:47]
	v_mfma_f32_16x16x32_bf16 v[44:47], v[132:135], v[212:215], v[44:47]
	v_mfma_f32_16x16x32_bf16 v[40:43], v[136:139], v[208:211], v[40:43]
	v_mfma_f32_16x16x32_bf16 v[40:43], v[140:143], v[212:215], v[40:43]
	v_mfma_f32_16x16x32_bf16 v[28:31], v[128:131], v[216:219], v[28:31]
	v_mfma_f32_16x16x32_bf16 v[28:31], v[132:135], v[220:223], v[28:31]
	v_mfma_f32_16x16x32_bf16 v[24:27], v[136:139], v[216:219], v[24:27]
	v_mfma_f32_16x16x32_bf16 v[24:27], v[140:143], v[220:223], v[24:27]
	v_mfma_f32_16x16x32_bf16 v[12:15], v[128:131], v[226:229], v[12:15]
	v_mfma_f32_16x16x32_bf16 v[12:15], v[132:135], v[230:233], v[12:15]
	v_mfma_f32_16x16x32_bf16 v[8:11], v[136:139], v[226:229], v[8:11]
	v_mfma_f32_16x16x32_bf16 v[8:11], v[140:143], v[230:233], v[8:11]
	s_setprio 0
	s_setprio 1
	v_mfma_f32_16x16x32_bf16 v[52:55], v[162:165], v[200:203], v[52:55]
	v_mfma_f32_16x16x32_bf16 v[52:55], v[188:191], v[204:207], v[52:55]
	v_mfma_f32_16x16x32_bf16 v[48:51], v[192:195], v[200:203], v[48:51]
	v_mfma_f32_16x16x32_bf16 v[48:51], v[196:199], v[204:207], v[48:51]
	v_mfma_f32_16x16x32_bf16 v[36:39], v[162:165], v[208:211], v[36:39]
	v_mfma_f32_16x16x32_bf16 v[36:39], v[188:191], v[212:215], v[36:39]
	v_mfma_f32_16x16x32_bf16 v[32:35], v[192:195], v[208:211], v[32:35]
	v_mfma_f32_16x16x32_bf16 v[32:35], v[196:199], v[212:215], v[32:35]
	v_mfma_f32_16x16x32_bf16 v[20:23], v[162:165], v[216:219], v[20:23]
	v_mfma_f32_16x16x32_bf16 v[20:23], v[188:191], v[220:223], v[20:23]
	v_mfma_f32_16x16x32_bf16 v[16:19], v[192:195], v[216:219], v[16:19]
	v_mfma_f32_16x16x32_bf16 v[16:19], v[196:199], v[220:223], v[16:19]
	v_mfma_f32_16x16x32_bf16 v[4:7], v[162:165], v[226:229], v[4:7]
	v_mfma_f32_16x16x32_bf16 v[4:7], v[188:191], v[230:233], v[4:7]
	v_mfma_f32_16x16x32_bf16 v[0:3], v[192:195], v[226:229], v[0:3]
	v_mfma_f32_16x16x32_bf16 v[0:3], v[196:199], v[230:233], v[0:3]
	s_setprio 0
	s_barrier
	s_add_i32 s24, 0, 0x18000
	s_add_i32 s25, 0, 0x1c000
	v_add_u32_e32 v140, s24, v168
	v_add_u32_e32 v152, s25, v168
	ds_read_b128 v[128:131], v140
	ds_read_b128 v[132:135], v140 offset:1024
	ds_read_b128 v[136:139], v140 offset:2048
	ds_read_b128 v[140:143], v140 offset:3072
	ds_read_b128 v[162:165], v152
	ds_read_b128 v[188:191], v152 offset:1024
	ds_read_b128 v[192:195], v152 offset:2048
	ds_read_b128 v[196:199], v152 offset:3072
	s_add_u32 s64, s64, 0x80000
	s_addc_u32 s65, s65, 0
	s_mov_b32 m0, s69
	v_lshl_add_u64 v[240:241], s[64:65], 0, v[144:145]
	ds_read_b128 v[200:203], v185 offset:32768
	ds_read_b128 v[204:207], v185 offset:33792
	ds_read_b128 v[208:211], v185 offset:34816
	ds_read_b128 v[212:215], v185 offset:35840
	ds_read_b128 v[216:219], v185 offset:36864
	ds_read_b128 v[220:223], v185 offset:37888
	ds_read_b128 v[226:229], v185 offset:38912
	ds_read_b128 v[230:233], v185 offset:39936
	global_load_lds_dwordx4 v[240:241], off
	v_lshl_add_u64 v[240:241], s[64:65], 0, v[148:149]
	s_mov_b32 m0, s70
	s_nop 0
	global_load_lds_dwordx4 v[240:241], off
	s_nop 0
	s_waitcnt vmcnt(8)
	s_waitcnt lgkmcnt(0)
	s_barrier
	s_setprio 1
	s_waitcnt lgkmcnt(0)
	v_mfma_f32_16x16x32_bf16 v[124:127], v[128:131], v[200:203], v[124:127]
	v_mfma_f32_16x16x32_bf16 v[124:127], v[132:135], v[204:207], v[124:127]
	v_mfma_f32_16x16x32_bf16 v[120:123], v[136:139], v[200:203], v[120:123]
	v_mfma_f32_16x16x32_bf16 v[120:123], v[140:143], v[204:207], v[120:123]
	v_mfma_f32_16x16x32_bf16 v[108:111], v[128:131], v[208:211], v[108:111]
	v_mfma_f32_16x16x32_bf16 v[108:111], v[132:135], v[212:215], v[108:111]
	v_mfma_f32_16x16x32_bf16 v[104:107], v[136:139], v[208:211], v[104:107]
	v_mfma_f32_16x16x32_bf16 v[104:107], v[140:143], v[212:215], v[104:107]
	v_mfma_f32_16x16x32_bf16 v[92:95], v[128:131], v[216:219], v[92:95]
	v_mfma_f32_16x16x32_bf16 v[92:95], v[132:135], v[220:223], v[92:95]
	v_mfma_f32_16x16x32_bf16 v[88:91], v[136:139], v[216:219], v[88:91]
	v_mfma_f32_16x16x32_bf16 v[88:91], v[140:143], v[220:223], v[88:91]
	v_mfma_f32_16x16x32_bf16 v[76:79], v[128:131], v[226:229], v[76:79]
	v_mfma_f32_16x16x32_bf16 v[76:79], v[132:135], v[230:233], v[76:79]
	v_mfma_f32_16x16x32_bf16 v[72:75], v[136:139], v[226:229], v[72:75]
	v_mfma_f32_16x16x32_bf16 v[72:75], v[140:143], v[230:233], v[72:75]
	s_setprio 0
	s_setprio 1
	v_mfma_f32_16x16x32_bf16 v[116:119], v[162:165], v[200:203], v[116:119]
	v_mfma_f32_16x16x32_bf16 v[116:119], v[188:191], v[204:207], v[116:119]
	v_mfma_f32_16x16x32_bf16 v[112:115], v[192:195], v[200:203], v[112:115]
	v_mfma_f32_16x16x32_bf16 v[112:115], v[196:199], v[204:207], v[112:115]
	v_mfma_f32_16x16x32_bf16 v[100:103], v[162:165], v[208:211], v[100:103]
	v_mfma_f32_16x16x32_bf16 v[100:103], v[188:191], v[212:215], v[100:103]
	v_mfma_f32_16x16x32_bf16 v[96:99], v[192:195], v[208:211], v[96:99]
	v_mfma_f32_16x16x32_bf16 v[96:99], v[196:199], v[212:215], v[96:99]
	v_mfma_f32_16x16x32_bf16 v[84:87], v[162:165], v[216:219], v[84:87]
	v_mfma_f32_16x16x32_bf16 v[84:87], v[188:191], v[220:223], v[84:87]
	v_mfma_f32_16x16x32_bf16 v[80:83], v[192:195], v[216:219], v[80:83]
	v_mfma_f32_16x16x32_bf16 v[80:83], v[196:199], v[220:223], v[80:83]
	v_mfma_f32_16x16x32_bf16 v[68:71], v[162:165], v[226:229], v[68:71]
	v_mfma_f32_16x16x32_bf16 v[68:71], v[188:191], v[230:233], v[68:71]
	v_mfma_f32_16x16x32_bf16 v[64:67], v[192:195], v[226:229], v[64:67]
	v_mfma_f32_16x16x32_bf16 v[64:67], v[196:199], v[230:233], v[64:67]
	s_setprio 0
	s_barrier
; #define PG8_STAGE(bufoff, gbase, voff) do { _Pragma("unroll") for (int _i = 0; _i < 2; ++_i) \
;         __builtin_amdgcn_global_load_lds((const unsigned*)((const char*)(gbase) + (voff)[_i]), (LAS unsigned*)(lds + (bufoff) + ldsw + _i * 8192), 16, 0, 0); } while (0)
; #define PG8_LDA(dst, b, h) do { _Pragma("unroll") for (int m = 0; m < 4; ++m) _Pragma("unroll") for (int k = 0; k < 2; ++k) dst[m][k] = *(const LAS bf16x8*)(lds + PG8_SA(b, h) + aoff + m * 2048 + k * 1024); } while (0)
; #define PG8_MMA(ai, bj, At, Bt) do { __builtin_amdgcn_s_setprio(1); _Pragma("unroll") for (int m = 0; m < 4; ++m) _Pragma("unroll") for (int n = 0; n < 2; ++n) _Pragma("unroll") for (int k = 0; k < 2; ++k) \
;         acc[ai][bj][m][n] = __builtin_amdgcn_mfma_f32_16x16x32_bf16(Bt[n][k], At[m][k], acc[ai][bj][m][n], 0, 0, 0); __builtin_amdgcn_s_setprio(0); } while (0)
; #define PG8_WAIT_V(n) asm volatile("s_waitcnt vmcnt(" #n ")" ::: "memory")
; #define PG8_WAIT_L(n) asm volatile("s_waitcnt lgkmcnt(" #n ")" ::: "memory")
; #define PG8_BAR __builtin_amdgcn_s_barrier()
; #define PG8_SCHED __builtin_amdgcn_sched_barrier(0)
; template <int FIXED_NT  , class Epi, class Sched>
; __device__ __forceinline__ void gemm_phase(LAS unsigned char* lds, const int tid_in, const int lda, const int ldb, const Sched& S, const Epi& E) {
;     ...
;             PG8_LDA(At, 1, 1); PG8_STAGE(PG8_SB(1, 0), b3, voffB); PG8_STAGE(PG8_SB(1, 1), b3 + hstepB, voffB); PG8_STAGE(PG8_SA(1, 0), a3, voffA);
;             PG8_WAIT_V(8); PG8_WAIT_L(0); PG8_BAR; PG8_MMA(1, 0, At, B0); PG8_MMA(1, 1, At, B1); PG8_BAR; PG8_SCHED;
;         }
	s_add_i32 s24, s24, s66
	v_lshl_add_u64 v[166:167], v[166:167], 0, s[18:19]
	s_mov_b32 m0, s24
	ds_read_b128 v[200:203], v185 offset:49152
	ds_read_b128 v[204:207], v185 offset:50176
	ds_read_b128 v[208:211], v185 offset:51200
	ds_read_b128 v[212:215], v185 offset:52224
	ds_read_b128 v[216:219], v185 offset:53248
	ds_read_b128 v[220:223], v185 offset:54272
	ds_read_b128 v[226:229], v185 offset:55296
	ds_read_b128 v[230:233], v185 offset:56320
	global_load_lds_dwordx4 v[166:167], off
	s_add_i32 m0, s24, 0x2000
	s_add_u32 s62, s62, 0x80080
	v_lshl_add_u64 v[166:167], v[234:235], 0, s[18:19]
	s_addc_u32 s63, s63, 0
	s_add_i32 s24, s25, s66
	global_load_lds_dwordx4 v[166:167], off
	v_lshl_add_u64 v[166:167], s[62:63], 0, v[146:147]
	s_mov_b32 m0, s24
	s_nop 0
	global_load_lds_dwordx4 v[166:167], off
	v_lshl_add_u64 v[166:167], s[62:63], 0, v[150:151]
	s_add_i32 m0, s24, 0x2000
	s_nop 0
	global_load_lds_dwordx4 v[166:167], off
	v_lshl_add_u64 v[166:167], v[236:237], 0, s[18:19]
	s_mov_b32 m0, s72
	s_nop 0
	global_load_lds_dwordx4 v[166:167], off
	v_lshl_add_u64 v[166:167], v[238:239], 0, s[18:19]
	s_mov_b32 m0, s73
	s_nop 0
	global_load_lds_dwordx4 v[166:167], off
	s_waitcnt vmcnt(8)
	s_waitcnt lgkmcnt(0)
	s_barrier
	s_setprio 1
	s_waitcnt lgkmcnt(0)
	v_mfma_f32_16x16x32_bf16 v[60:63], v[128:131], v[200:203], v[60:63]
	v_mfma_f32_16x16x32_bf16 v[60:63], v[132:135], v[204:207], v[60:63]
	v_mfma_f32_16x16x32_bf16 v[56:59], v[136:139], v[200:203], v[56:59]
	v_mfma_f32_16x16x32_bf16 v[56:59], v[140:143], v[204:207], v[56:59]
	v_mfma_f32_16x16x32_bf16 v[44:47], v[128:131], v[208:211], v[44:47]
	v_mfma_f32_16x16x32_bf16 v[44:47], v[132:135], v[212:215], v[44:47]
	v_mfma_f32_16x16x32_bf16 v[40:43], v[136:139], v[208:211], v[40:43]
	v_mfma_f32_16x16x32_bf16 v[40:43], v[140:143], v[212:215], v[40:43]
	v_mfma_f32_16x16x32_bf16 v[28:31], v[128:131], v[216:219], v[28:31]
	v_mfma_f32_16x16x32_bf16 v[28:31], v[132:135], v[220:223], v[28:31]
	v_mfma_f32_16x16x32_bf16 v[24:27], v[136:139], v[216:219], v[24:27]
	v_mfma_f32_16x16x32_bf16 v[24:27], v[140:143], v[220:223], v[24:27]
	v_mfma_f32_16x16x32_bf16 v[12:15], v[128:131], v[226:229], v[12:15]
	v_mfma_f32_16x16x32_bf16 v[12:15], v[132:135], v[230:233], v[12:15]
	v_mfma_f32_16x16x32_bf16 v[8:11], v[136:139], v[226:229], v[8:11]
	v_mfma_f32_16x16x32_bf16 v[8:11], v[140:143], v[230:233], v[8:11]
	s_setprio 0
	s_setprio 1
	v_mfma_f32_16x16x32_bf16 v[52:55], v[162:165], v[200:203], v[52:55]
	v_mfma_f32_16x16x32_bf16 v[52:55], v[188:191], v[204:207], v[52:55]
	v_mfma_f32_16x16x32_bf16 v[48:51], v[192:195], v[200:203], v[48:51]
	v_mfma_f32_16x16x32_bf16 v[48:51], v[196:199], v[204:207], v[48:51]
	v_mfma_f32_16x16x32_bf16 v[36:39], v[162:165], v[208:211], v[36:39]
	v_mfma_f32_16x16x32_bf16 v[36:39], v[188:191], v[212:215], v[36:39]
	v_mfma_f32_16x16x32_bf16 v[32:35], v[192:195], v[208:211], v[32:35]
	v_mfma_f32_16x16x32_bf16 v[32:35], v[196:199], v[212:215], v[32:35]
	v_mfma_f32_16x16x32_bf16 v[20:23], v[162:165], v[216:219], v[20:23]
	v_mfma_f32_16x16x32_bf16 v[20:23], v[188:191], v[220:223], v[20:23]
	v_mfma_f32_16x16x32_bf16 v[16:19], v[192:195], v[216:219], v[16:19]
	v_mfma_f32_16x16x32_bf16 v[16:19], v[196:199], v[220:223], v[16:19]
	v_mfma_f32_16x16x32_bf16 v[4:7], v[162:165], v[226:229], v[4:7]
	v_mfma_f32_16x16x32_bf16 v[4:7], v[188:191], v[230:233], v[4:7]
	v_mfma_f32_16x16x32_bf16 v[0:3], v[192:195], v[226:229], v[0:3]
	v_mfma_f32_16x16x32_bf16 v[0:3], v[196:199], v[230:233], v[0:3]
	s_setprio 0
	s_barrier
	s_add_u32 s6, s6, 0x100
	s_addc_u32 s7, s7, 0
	s_add_u32 s14, s14, 0x100
	s_addc_u32 s53, s53, 0
	s_cmp_ge_i32 s79, s35
	s_mov_b32 s57, s79
	s_cbranch_scc0 .LBB0_244
	s_and_b64 vcc, exec, s[22:23]
	s_cbranch_vccz .LBB0_250

; #define PG8_STAGE(bufoff, gbase, voff) do { _Pragma("unroll") for (int _i = 0; _i < 2; ++_i) \
;         __builtin_amdgcn_global_load_lds((const unsigned*)((const char*)(gbase) + (voff)[_i]), (LAS unsigned*)(lds + (bufoff) + ldsw + _i * 8192), 16, 0, 0); } while (0)
; #define PG8_LDA(dst, b, h) do { _Pragma("unroll") for (int m = 0; m < 4; ++m) _Pragma("unroll") for (int k = 0; k < 2; ++k) dst[m][k] = *(const LAS bf16x8*)(lds + PG8_SA(b, h) + aoff + m * 2048 + k * 1024); } while (0)
; #define PG8_LDB(dst, b, h) do { _Pragma("unroll") for (int n = 0; n < 2; ++n) _Pragma("unroll") for (int k = 0; k < 2; ++k) dst[n][k] = *(const LAS bf16x8*)(lds + PG8_SB(b, h) + boff + n * 2048 + k * 1024); } while (0)
; #define PG8_MMA(ai, bj, At, Bt) do { __builtin_amdgcn_s_setprio(1); _Pragma("unroll") for (int m = 0; m < 4; ++m) _Pragma("unroll") for (int n = 0; n < 2; ++n) _Pragma("unroll") for (int k = 0; k < 2; ++k) \
;         acc[ai][bj][m][n] = __builtin_amdgcn_mfma_f32_16x16x32_bf16(Bt[n][k], At[m][k], acc[ai][bj][m][n], 0, 0, 0); __builtin_amdgcn_s_setprio(0); } while (0)
; #define PG8_WAIT_V(n) asm volatile("s_waitcnt vmcnt(" #n ")" ::: "memory")
; #define PG8_WAIT_L(n) asm volatile("s_waitcnt lgkmcnt(" #n ")" ::: "memory")
; #define PG8_BAR __builtin_amdgcn_s_barrier()
; #define PG8_SCHED __builtin_amdgcn_sched_barrier(0)
; template <int FIXED_NT  , class Epi, class Sched>
; __device__ __forceinline__ void gemm_phase(LAS unsigned char* lds, const int tid_in, const int lda, const int ldb, const Sched& S, const Epi& E) {
;     ...
;         for (int t = 0; t < nt; t += 2) {
;             const bool last = (t == nt - 2);
;             const char* a1 = cA + (size_t)(t + 1) * kstep;
;             const char* a2 = last ? nA : cA + (size_t)(t + 2) * kstep; const char* b2 = last ? nB : cB + (size_t)(t + 2) * kstep;
;             const char* a3 = a2 + kstep; const char* b3 = b2 + kstep;
;             PG8_LDB(B0, 0, 0); PG8_LDB(B1, 0, 1); PG8_SCHED; PG8_LDA(At, 0, 0); PG8_STAGE(PG8_SA(1, 1), a1 + hstepA, voffA);
;             PG8_WAIT_V(8); PG8_WAIT_L(0); PG8_BAR; PG8_MMA(0, 0, At, B0); PG8_MMA(0, 1, At, B1); PG8_BAR; PG8_SCHED;
;             PG8_LDA(At, 0, 1); PG8_STAGE(PG8_SB(0, 0), b2, voffB); PG8_STAGE(PG8_SB(0, 1), b2 + hstepB, voffB); PG8_STAGE(PG8_SA(0, 0), a2, voffA);
.LBB0_598:
	ds_read_b128 v[128:131], v167
	ds_read_b128 v[132:135], v167 offset:1024
	ds_read_b128 v[148:151], v167 offset:2048
	ds_read_b128 v[152:155], v167 offset:3072
	ds_read_b128 v[156:159], v168
	ds_read_b128 v[160:163], v168 offset:1024
	ds_read_b128 v[170:173], v168 offset:2048
	ds_read_b128 v[174:177], v168 offset:3072
	s_add_i32 s73, s30, 2
	s_add_u32 s31, s28, 0xfffc0080
	s_addc_u32 s54, s29, -1
	s_cmp_eq_u32 s64, s30
	s_cselect_b32 s30, s22, s17
	s_cselect_b32 s55, s21, s54
	s_cselect_b32 s54, s20, s31
	s_cselect_b32 s31, s23, s72
	s_mov_b32 m0, s65
	v_lshl_add_u64 v[210:211], s[28:29], 0, v[144:145]
	ds_read_b128 v[178:181], v169
	ds_read_b128 v[182:185], v169 offset:1024
	ds_read_b128 v[186:189], v169 offset:2048
	ds_read_b128 v[190:193], v169 offset:3072
	ds_read_b128 v[194:197], v169 offset:4096
	ds_read_b128 v[198:201], v169 offset:5120
	ds_read_b128 v[202:205], v169 offset:6144
	ds_read_b128 v[206:209], v169 offset:7168
	global_load_lds_dwordx4 v[210:211], off
	v_lshl_add_u64 v[210:211], s[28:29], 0, v[146:147]
	s_mov_b32 m0, s66
	s_nop 0
	global_load_lds_dwordx4 v[210:211], off
	s_nop 0
	s_waitcnt vmcnt(8)
	s_waitcnt lgkmcnt(0)
	s_barrier
	s_setprio 1
	s_waitcnt lgkmcnt(0)
	v_mfma_f32_16x16x32_bf16 v[124:127], v[128:131], v[178:181], v[124:127]
	v_mfma_f32_16x16x32_bf16 v[124:127], v[132:135], v[182:185], v[124:127]
	v_mfma_f32_16x16x32_bf16 v[120:123], v[148:151], v[178:181], v[120:123]
	v_mfma_f32_16x16x32_bf16 v[120:123], v[152:155], v[182:185], v[120:123]
	v_mfma_f32_16x16x32_bf16 v[116:119], v[128:131], v[186:189], v[116:119]
	v_mfma_f32_16x16x32_bf16 v[116:119], v[132:135], v[190:193], v[116:119]
	v_mfma_f32_16x16x32_bf16 v[112:115], v[148:151], v[186:189], v[112:115]
	v_mfma_f32_16x16x32_bf16 v[112:115], v[152:155], v[190:193], v[112:115]
	v_mfma_f32_16x16x32_bf16 v[108:111], v[128:131], v[194:197], v[108:111]
	v_mfma_f32_16x16x32_bf16 v[108:111], v[132:135], v[198:201], v[108:111]
	v_mfma_f32_16x16x32_bf16 v[104:107], v[148:151], v[194:197], v[104:107]
	v_mfma_f32_16x16x32_bf16 v[104:107], v[152:155], v[198:201], v[104:107]
	v_mfma_f32_16x16x32_bf16 v[100:103], v[128:131], v[202:205], v[100:103]
	v_mfma_f32_16x16x32_bf16 v[100:103], v[132:135], v[206:209], v[100:103]
	v_mfma_f32_16x16x32_bf16 v[96:99], v[148:151], v[202:205], v[96:99]
	v_mfma_f32_16x16x32_bf16 v[96:99], v[152:155], v[206:209], v[96:99]
	s_setprio 0
	s_setprio 1
	v_mfma_f32_16x16x32_bf16 v[60:63], v[156:159], v[178:181], v[60:63]
	v_mfma_f32_16x16x32_bf16 v[60:63], v[160:163], v[182:185], v[60:63]
	v_mfma_f32_16x16x32_bf16 v[56:59], v[170:173], v[178:181], v[56:59]
	v_mfma_f32_16x16x32_bf16 v[56:59], v[174:177], v[182:185], v[56:59]
	v_mfma_f32_16x16x32_bf16 v[52:55], v[156:159], v[186:189], v[52:55]
	v_mfma_f32_16x16x32_bf16 v[52:55], v[160:163], v[190:193], v[52:55]
	v_mfma_f32_16x16x32_bf16 v[48:51], v[170:173], v[186:189], v[48:51]
	v_mfma_f32_16x16x32_bf16 v[48:51], v[174:177], v[190:193], v[48:51]
	v_mfma_f32_16x16x32_bf16 v[44:47], v[156:159], v[194:197], v[44:47]
	v_mfma_f32_16x16x32_bf16 v[44:47], v[160:163], v[198:201], v[44:47]
	v_mfma_f32_16x16x32_bf16 v[40:43], v[170:173], v[194:197], v[40:43]
	v_mfma_f32_16x16x32_bf16 v[40:43], v[174:177], v[198:201], v[40:43]
	v_mfma_f32_16x16x32_bf16 v[36:39], v[156:159], v[202:205], v[36:39]
	v_mfma_f32_16x16x32_bf16 v[36:39], v[160:163], v[206:209], v[36:39]
	v_mfma_f32_16x16x32_bf16 v[32:35], v[170:173], v[202:205], v[32:35]
	v_mfma_f32_16x16x32_bf16 v[32:35], v[174:177], v[206:209], v[32:35]
	s_setprio 0
	s_barrier
	s_mov_b32 m0, s67
	v_lshl_add_u64 v[210:211], s[30:31], 0, v[140:141]
	s_add_u32 s88, s30, 0x10000
	ds_read_b128 v[178:181], v169 offset:16384
	ds_read_b128 v[182:185], v169 offset:17408
	ds_read_b128 v[186:189], v169 offset:18432
	ds_read_b128 v[190:193], v169 offset:19456
	ds_read_b128 v[194:197], v169 offset:20480
	ds_read_b128 v[198:201], v169 offset:21504
	ds_read_b128 v[202:205], v169 offset:22528
	ds_read_b128 v[206:209], v169 offset:23552
	global_load_lds_dwordx4 v[210:211], off
	v_lshl_add_u64 v[212:213], s[30:31], 0, v[136:137]
	s_mov_b32 m0, s68
	s_addc_u32 s89, s31, 0
	global_load_lds_dwordx4 v[212:213], off
	v_lshl_add_u64 v[214:215], s[88:89], 0, v[140:141]
	s_mov_b32 m0, s69
	v_lshl_add_u64 v[216:217], s[54:55], 0, v[138:139]
	global_load_lds_dwordx4 v[214:215], off
	v_lshl_add_u64 v[214:215], s[88:89], 0, v[136:137]
	s_add_i32 m0, s69, 0x2000
	s_nop 0
	global_load_lds_dwordx4 v[214:215], off
	v_lshl_add_u64 v[214:215], s[54:55], 0, v[142:143]
	s_mov_b32 m0, s25
	s_nop 0
	global_load_lds_dwordx4 v[214:215], off
	s_mov_b32 m0, s58
	s_nop 0
	global_load_lds_dwordx4 v[216:217], off
	s_waitcnt vmcnt(8)
	s_waitcnt lgkmcnt(0)
	s_barrier
; #define PG8_STAGE(bufoff, gbase, voff) do { _Pragma("unroll") for (int _i = 0; _i < 2; ++_i) \
;         __builtin_amdgcn_global_load_lds((const unsigned*)((const char*)(gbase) + (voff)[_i]), (LAS unsigned*)(lds + (bufoff) + ldsw + _i * 8192), 16, 0, 0); } while (0)
; #define PG8_LDA(dst, b, h) do { _Pragma("unroll") for (int m = 0; m < 4; ++m) _Pragma("unroll") for (int k = 0; k < 2; ++k) dst[m][k] = *(const LAS bf16x8*)(lds + PG8_SA(b, h) + aoff + m * 2048 + k * 1024); } while (0)
; #define PG8_LDB(dst, b, h) do { _Pragma("unroll") for (int n = 0; n < 2; ++n) _Pragma("unroll") for (int k = 0; k < 2; ++k) dst[n][k] = *(const LAS bf16x8*)(lds + PG8_SB(b, h) + boff + n * 2048 + k * 1024); } while (0)
; #define PG8_MMA(ai, bj, At, Bt) do { __builtin_amdgcn_s_setprio(1); _Pragma("unroll") for (int m = 0; m < 4; ++m) _Pragma("unroll") for (int n = 0; n < 2; ++n) _Pragma("unroll") for (int k = 0; k < 2; ++k) \
;         acc[ai][bj][m][n] = __builtin_amdgcn_mfma_f32_16x16x32_bf16(Bt[n][k], At[m][k], acc[ai][bj][m][n], 0, 0, 0); __builtin_amdgcn_s_setprio(0); } while (0)
; #define PG8_WAIT_V(n) asm volatile("s_waitcnt vmcnt(" #n ")" ::: "memory")
; #define PG8_WAIT_L(n) asm volatile("s_waitcnt lgkmcnt(" #n ")" ::: "memory")
; #define PG8_BAR __builtin_amdgcn_s_barrier()
; #define PG8_SCHED __builtin_amdgcn_sched_barrier(0)
; template <int FIXED_NT  , class Epi, class Sched>
; __device__ __forceinline__ void gemm_phase(LAS unsigned char* lds, const int tid_in, const int lda, const int ldb, const Sched& S, const Epi& E) {
;     ...
;             PG8_WAIT_V(8); PG8_WAIT_L(0); PG8_BAR; PG8_MMA(1, 0, At, B0); PG8_MMA(1, 1, At, B1); PG8_BAR; PG8_SCHED;
;             PG8_LDB(B0, 1, 0); PG8_LDB(B1, 1, 1); PG8_SCHED; PG8_LDA(At, 1, 0); PG8_STAGE(PG8_SA(0, 1), a2 + hstepA, voffA);
;             PG8_WAIT_V(8); PG8_WAIT_L(0); PG8_BAR; PG8_MMA(0, 0, At, B0); PG8_MMA(0, 1, At, B1); PG8_BAR; PG8_SCHED;
	s_setprio 1
	s_waitcnt lgkmcnt(0)
	v_mfma_f32_16x16x32_bf16 v[92:95], v[128:131], v[178:181], v[92:95]
	v_mfma_f32_16x16x32_bf16 v[92:95], v[132:135], v[182:185], v[92:95]
	v_mfma_f32_16x16x32_bf16 v[88:91], v[148:151], v[178:181], v[88:91]
	v_mfma_f32_16x16x32_bf16 v[88:91], v[152:155], v[182:185], v[88:91]
	v_mfma_f32_16x16x32_bf16 v[84:87], v[128:131], v[186:189], v[84:87]
	v_mfma_f32_16x16x32_bf16 v[84:87], v[132:135], v[190:193], v[84:87]
	v_mfma_f32_16x16x32_bf16 v[80:83], v[148:151], v[186:189], v[80:83]
	v_mfma_f32_16x16x32_bf16 v[80:83], v[152:155], v[190:193], v[80:83]
	v_mfma_f32_16x16x32_bf16 v[76:79], v[128:131], v[194:197], v[76:79]
	v_mfma_f32_16x16x32_bf16 v[76:79], v[132:135], v[198:201], v[76:79]
	v_mfma_f32_16x16x32_bf16 v[72:75], v[148:151], v[194:197], v[72:75]
	v_mfma_f32_16x16x32_bf16 v[72:75], v[152:155], v[198:201], v[72:75]
	v_mfma_f32_16x16x32_bf16 v[68:71], v[128:131], v[202:205], v[68:71]
	v_mfma_f32_16x16x32_bf16 v[68:71], v[132:135], v[206:209], v[68:71]
	v_mfma_f32_16x16x32_bf16 v[64:67], v[148:151], v[202:205], v[64:67]
	v_mfma_f32_16x16x32_bf16 v[64:67], v[152:155], v[206:209], v[64:67]
	s_setprio 0
	s_setprio 1
	v_mfma_f32_16x16x32_bf16 v[28:31], v[156:159], v[178:181], v[28:31]
	v_mfma_f32_16x16x32_bf16 v[28:31], v[160:163], v[182:185], v[28:31]
	v_mfma_f32_16x16x32_bf16 v[24:27], v[170:173], v[178:181], v[24:27]
	v_mfma_f32_16x16x32_bf16 v[24:27], v[174:177], v[182:185], v[24:27]
	v_mfma_f32_16x16x32_bf16 v[20:23], v[156:159], v[186:189], v[20:23]
	v_mfma_f32_16x16x32_bf16 v[20:23], v[160:163], v[190:193], v[20:23]
	v_mfma_f32_16x16x32_bf16 v[16:19], v[170:173], v[186:189], v[16:19]
	v_mfma_f32_16x16x32_bf16 v[16:19], v[174:177], v[190:193], v[16:19]
	v_mfma_f32_16x16x32_bf16 v[12:15], v[156:159], v[194:197], v[12:15]
	v_mfma_f32_16x16x32_bf16 v[12:15], v[160:163], v[198:201], v[12:15]
	v_mfma_f32_16x16x32_bf16 v[8:11], v[170:173], v[194:197], v[8:11]
	v_mfma_f32_16x16x32_bf16 v[8:11], v[174:177], v[198:201], v[8:11]
	v_mfma_f32_16x16x32_bf16 v[4:7], v[156:159], v[202:205], v[4:7]
	v_mfma_f32_16x16x32_bf16 v[4:7], v[160:163], v[206:209], v[4:7]
	v_mfma_f32_16x16x32_bf16 v[0:3], v[170:173], v[202:205], v[0:3]
	v_mfma_f32_16x16x32_bf16 v[0:3], v[174:177], v[206:209], v[0:3]
	s_setprio 0
	s_barrier
	s_add_i32 s74, 0, 0x18000
	s_add_i32 s76, 0, 0x1c000
	v_add_u32_e32 v152, s74, v165
	v_add_u32_e32 v174, s76, v165
	ds_read_b128 v[128:131], v152
	ds_read_b128 v[132:135], v152 offset:1024
	ds_read_b128 v[148:151], v152 offset:2048
	ds_read_b128 v[152:155], v152 offset:3072
	ds_read_b128 v[156:159], v174
	ds_read_b128 v[160:163], v174 offset:1024
	ds_read_b128 v[170:173], v174 offset:2048
	ds_read_b128 v[174:177], v174 offset:3072
	s_add_u32 s54, s54, 0x40000
	s_addc_u32 s55, s55, 0
	s_mov_b32 m0, s59
	v_lshl_add_u64 v[218:219], s[54:55], 0, v[142:143]
	ds_read_b128 v[178:181], v169 offset:32768
	ds_read_b128 v[182:185], v169 offset:33792
	ds_read_b128 v[186:189], v169 offset:34816
	ds_read_b128 v[190:193], v169 offset:35840
	ds_read_b128 v[194:197], v169 offset:36864
	ds_read_b128 v[198:201], v169 offset:37888
	ds_read_b128 v[202:205], v169 offset:38912
	ds_read_b128 v[206:209], v169 offset:39936
	global_load_lds_dwordx4 v[218:219], off
	v_lshl_add_u64 v[218:219], s[54:55], 0, v[138:139]
	s_mov_b32 m0, s60
	s_nop 0
	global_load_lds_dwordx4 v[218:219], off
	s_nop 0
	s_waitcnt vmcnt(8)
	s_waitcnt lgkmcnt(0)
	s_barrier
	s_setprio 1
	s_waitcnt lgkmcnt(0)
	v_mfma_f32_16x16x32_bf16 v[124:127], v[128:131], v[178:181], v[124:127]
	v_mfma_f32_16x16x32_bf16 v[124:127], v[132:135], v[182:185], v[124:127]
	v_mfma_f32_16x16x32_bf16 v[120:123], v[148:151], v[178:181], v[120:123]
	v_mfma_f32_16x16x32_bf16 v[120:123], v[152:155], v[182:185], v[120:123]
	v_mfma_f32_16x16x32_bf16 v[116:119], v[128:131], v[186:189], v[116:119]
	v_mfma_f32_16x16x32_bf16 v[116:119], v[132:135], v[190:193], v[116:119]
	v_mfma_f32_16x16x32_bf16 v[112:115], v[148:151], v[186:189], v[112:115]
	v_mfma_f32_16x16x32_bf16 v[112:115], v[152:155], v[190:193], v[112:115]
	v_mfma_f32_16x16x32_bf16 v[108:111], v[128:131], v[194:197], v[108:111]
	v_mfma_f32_16x16x32_bf16 v[108:111], v[132:135], v[198:201], v[108:111]
	v_mfma_f32_16x16x32_bf16 v[104:107], v[148:151], v[194:197], v[104:107]
	v_mfma_f32_16x16x32_bf16 v[104:107], v[152:155], v[198:201], v[104:107]
	v_mfma_f32_16x16x32_bf16 v[100:103], v[128:131], v[202:205], v[100:103]
	v_mfma_f32_16x16x32_bf16 v[100:103], v[132:135], v[206:209], v[100:103]
	v_mfma_f32_16x16x32_bf16 v[96:99], v[148:151], v[202:205], v[96:99]
	v_mfma_f32_16x16x32_bf16 v[96:99], v[152:155], v[206:209], v[96:99]
	s_setprio 0
	s_setprio 1
	v_mfma_f32_16x16x32_bf16 v[60:63], v[156:159], v[178:181], v[60:63]
	v_mfma_f32_16x16x32_bf16 v[60:63], v[160:163], v[182:185], v[60:63]
	v_mfma_f32_16x16x32_bf16 v[56:59], v[170:173], v[178:181], v[56:59]
	v_mfma_f32_16x16x32_bf16 v[56:59], v[174:177], v[182:185], v[56:59]
	v_mfma_f32_16x16x32_bf16 v[52:55], v[156:159], v[186:189], v[52:55]
	v_mfma_f32_16x16x32_bf16 v[52:55], v[160:163], v[190:193], v[52:55]
	v_mfma_f32_16x16x32_bf16 v[48:51], v[170:173], v[186:189], v[48:51]
	v_mfma_f32_16x16x32_bf16 v[48:51], v[174:177], v[190:193], v[48:51]
	v_mfma_f32_16x16x32_bf16 v[44:47], v[156:159], v[194:197], v[44:47]
	v_mfma_f32_16x16x32_bf16 v[44:47], v[160:163], v[198:201], v[44:47]
	v_mfma_f32_16x16x32_bf16 v[40:43], v[170:173], v[194:197], v[40:43]
	v_mfma_f32_16x16x32_bf16 v[40:43], v[174:177], v[198:201], v[40:43]
	v_mfma_f32_16x16x32_bf16 v[36:39], v[156:159], v[202:205], v[36:39]
	v_mfma_f32_16x16x32_bf16 v[36:39], v[160:163], v[206:209], v[36:39]
	v_mfma_f32_16x16x32_bf16 v[32:35], v[170:173], v[202:205], v[32:35]
	v_mfma_f32_16x16x32_bf16 v[32:35], v[174:177], v[206:209], v[32:35]
	s_setprio 0
	s_barrier
; #define PG8_STAGE(bufoff, gbase, voff) do { _Pragma("unroll") for (int _i = 0; _i < 2; ++_i) \
;         __builtin_amdgcn_global_load_lds((const unsigned*)((const char*)(gbase) + (voff)[_i]), (LAS unsigned*)(lds + (bufoff) + ldsw + _i * 8192), 16, 0, 0); } while (0)
; #define PG8_LDA(dst, b, h) do { _Pragma("unroll") for (int m = 0; m < 4; ++m) _Pragma("unroll") for (int k = 0; k < 2; ++k) dst[m][k] = *(const LAS bf16x8*)(lds + PG8_SA(b, h) + aoff + m * 2048 + k * 1024); } while (0)
; #define PG8_MMA(ai, bj, At, Bt) do { __builtin_amdgcn_s_setprio(1); _Pragma("unroll") for (int m = 0; m < 4; ++m) _Pragma("unroll") for (int n = 0; n < 2; ++n) _Pragma("unroll") for (int k = 0; k < 2; ++k) \
;         acc[ai][bj][m][n] = __builtin_amdgcn_mfma_f32_16x16x32_bf16(Bt[n][k], At[m][k], acc[ai][bj][m][n], 0, 0, 0); __builtin_amdgcn_s_setprio(0); } while (0)
; #define PG8_WAIT_V(n) asm volatile("s_waitcnt vmcnt(" #n ")" ::: "memory")
; #define PG8_WAIT_L(n) asm volatile("s_waitcnt lgkmcnt(" #n ")" ::: "memory")
; #define PG8_BAR __builtin_amdgcn_s_barrier()
; #define PG8_SCHED __builtin_amdgcn_sched_barrier(0)
; template <int FIXED_NT  , class Epi, class Sched>
; __device__ __forceinline__ void gemm_phase(LAS unsigned char* lds, const int tid_in, const int lda, const int ldb, const Sched& S, const Epi& E) {
;     ...
;             PG8_LDA(At, 1, 1); PG8_STAGE(PG8_SB(1, 0), b3, voffB); PG8_STAGE(PG8_SB(1, 1), b3 + hstepB, voffB); PG8_STAGE(PG8_SA(1, 0), a3, voffA);
;             PG8_WAIT_V(8); PG8_WAIT_L(0); PG8_BAR; PG8_MMA(1, 0, At, B0); PG8_MMA(1, 1, At, B1); PG8_BAR; PG8_SCHED;
;         }
	s_add_i32 s54, s74, s45
	v_lshl_add_u64 v[210:211], v[210:211], 0, s[10:11]
	s_mov_b32 m0, s54
	ds_read_b128 v[178:181], v169 offset:49152
	ds_read_b128 v[182:185], v169 offset:50176
	ds_read_b128 v[186:189], v169 offset:51200
	ds_read_b128 v[190:193], v169 offset:52224
	ds_read_b128 v[194:197], v169 offset:53248
	ds_read_b128 v[198:201], v169 offset:54272
	ds_read_b128 v[202:205], v169 offset:55296
	ds_read_b128 v[206:209], v169 offset:56320
	global_load_lds_dwordx4 v[210:211], off
	s_add_i32 m0, s54, 0x2000
	s_add_u32 s30, s30, 0x10080
	v_lshl_add_u64 v[210:211], v[212:213], 0, s[10:11]
	s_addc_u32 s31, s31, 0
	s_add_i32 s54, s76, s45
	global_load_lds_dwordx4 v[210:211], off
	v_lshl_add_u64 v[210:211], s[30:31], 0, v[140:141]
	s_mov_b32 m0, s54
	s_nop 0
	global_load_lds_dwordx4 v[210:211], off
	v_lshl_add_u64 v[210:211], s[30:31], 0, v[136:137]
	s_add_i32 m0, s54, 0x2000
	s_nop 0
	global_load_lds_dwordx4 v[210:211], off
	v_lshl_add_u64 v[210:211], v[214:215], 0, s[10:11]
	s_mov_b32 m0, s62
	s_nop 0
	global_load_lds_dwordx4 v[210:211], off
	v_lshl_add_u64 v[210:211], v[216:217], 0, s[10:11]
	s_mov_b32 m0, s63
	s_nop 0
	global_load_lds_dwordx4 v[210:211], off
	s_waitcnt vmcnt(8)
	s_waitcnt lgkmcnt(0)
	s_barrier
	s_setprio 1
	s_waitcnt lgkmcnt(0)
	v_mfma_f32_16x16x32_bf16 v[92:95], v[128:131], v[178:181], v[92:95]
	v_mfma_f32_16x16x32_bf16 v[92:95], v[132:135], v[182:185], v[92:95]
	v_mfma_f32_16x16x32_bf16 v[88:91], v[148:151], v[178:181], v[88:91]
	v_mfma_f32_16x16x32_bf16 v[88:91], v[152:155], v[182:185], v[88:91]
	v_mfma_f32_16x16x32_bf16 v[84:87], v[128:131], v[186:189], v[84:87]
	v_mfma_f32_16x16x32_bf16 v[84:87], v[132:135], v[190:193], v[84:87]
	v_mfma_f32_16x16x32_bf16 v[80:83], v[148:151], v[186:189], v[80:83]
	v_mfma_f32_16x16x32_bf16 v[80:83], v[152:155], v[190:193], v[80:83]
	v_mfma_f32_16x16x32_bf16 v[76:79], v[128:131], v[194:197], v[76:79]
	v_mfma_f32_16x16x32_bf16 v[76:79], v[132:135], v[198:201], v[76:79]
	v_mfma_f32_16x16x32_bf16 v[72:75], v[148:151], v[194:197], v[72:75]
	v_mfma_f32_16x16x32_bf16 v[72:75], v[152:155], v[198:201], v[72:75]
	v_mfma_f32_16x16x32_bf16 v[68:71], v[128:131], v[202:205], v[68:71]
	v_mfma_f32_16x16x32_bf16 v[68:71], v[132:135], v[206:209], v[68:71]
	v_mfma_f32_16x16x32_bf16 v[64:67], v[148:151], v[202:205], v[64:67]
	v_mfma_f32_16x16x32_bf16 v[64:67], v[152:155], v[206:209], v[64:67]
	s_setprio 0
	s_setprio 1
	v_mfma_f32_16x16x32_bf16 v[28:31], v[156:159], v[178:181], v[28:31]
	v_mfma_f32_16x16x32_bf16 v[28:31], v[160:163], v[182:185], v[28:31]
	v_mfma_f32_16x16x32_bf16 v[24:27], v[170:173], v[178:181], v[24:27]
	v_mfma_f32_16x16x32_bf16 v[24:27], v[174:177], v[182:185], v[24:27]
	v_mfma_f32_16x16x32_bf16 v[20:23], v[156:159], v[186:189], v[20:23]
	v_mfma_f32_16x16x32_bf16 v[20:23], v[160:163], v[190:193], v[20:23]
	v_mfma_f32_16x16x32_bf16 v[16:19], v[170:173], v[186:189], v[16:19]
	v_mfma_f32_16x16x32_bf16 v[16:19], v[174:177], v[190:193], v[16:19]
	v_mfma_f32_16x16x32_bf16 v[12:15], v[156:159], v[194:197], v[12:15]
	v_mfma_f32_16x16x32_bf16 v[12:15], v[160:163], v[198:201], v[12:15]
	v_mfma_f32_16x16x32_bf16 v[8:11], v[170:173], v[194:197], v[8:11]
	v_mfma_f32_16x16x32_bf16 v[8:11], v[174:177], v[198:201], v[8:11]
	v_mfma_f32_16x16x32_bf16 v[4:7], v[156:159], v[202:205], v[4:7]
	v_mfma_f32_16x16x32_bf16 v[4:7], v[160:163], v[206:209], v[4:7]
	v_mfma_f32_16x16x32_bf16 v[0:3], v[170:173], v[202:205], v[0:3]
	v_mfma_f32_16x16x32_bf16 v[0:3], v[174:177], v[206:209], v[0:3]
	s_setprio 0
	s_barrier
	s_add_u32 s28, s28, 0x100
	s_addc_u32 s29, s29, 0
	s_add_u32 s17, s17, 0x100
	s_addc_u32 s72, s72, 0
	s_cmp_ge_i32 s73, s33
	s_mov_b32 s30, s73
	s_cbranch_scc0 .LBB0_598
	s_and_b64 vcc, exec, s[14:15]
	s_cbranch_vccz .LBB0_601

; #define PG8_STAGE(bufoff, gbase, voff) do { _Pragma("unroll") for (int _i = 0; _i < 2; ++_i) \
;         __builtin_amdgcn_global_load_lds((const unsigned*)((const char*)(gbase) + (voff)[_i]), (LAS unsigned*)(lds + (bufoff) + ldsw + _i * 8192), 16, 0, 0); } while (0)
; #define PG8_LDA(dst, b, h) do { _Pragma("unroll") for (int m = 0; m < 4; ++m) _Pragma("unroll") for (int k = 0; k < 2; ++k) dst[m][k] = *(const LAS bf16x8*)(lds + PG8_SA(b, h) + aoff + m * 2048 + k * 1024); } while (0)
; #define PG8_LDB(dst, b, h) do { _Pragma("unroll") for (int n = 0; n < 2; ++n) _Pragma("unroll") for (int k = 0; k < 2; ++k) dst[n][k] = *(const LAS bf16x8*)(lds + PG8_SB(b, h) + boff + n * 2048 + k * 1024); } while (0)
; #define PG8_MMA(ai, bj, At, Bt) do { __builtin_amdgcn_s_setprio(1); _Pragma("unroll") for (int m = 0; m < 4; ++m) _Pragma("unroll") for (int n = 0; n < 2; ++n) _Pragma("unroll") for (int k = 0; k < 2; ++k) \
;         acc[ai][bj][m][n] = __builtin_amdgcn_mfma_f32_16x16x32_bf16(Bt[n][k], At[m][k], acc[ai][bj][m][n], 0, 0, 0); __builtin_amdgcn_s_setprio(0); } while (0)
; #define PG8_WAIT_V(n) asm volatile("s_waitcnt vmcnt(" #n ")" ::: "memory")
; #define PG8_WAIT_L(n) asm volatile("s_waitcnt lgkmcnt(" #n ")" ::: "memory")
; #define PG8_BAR __builtin_amdgcn_s_barrier()
; #define PG8_SCHED __builtin_amdgcn_sched_barrier(0)
; template <int FIXED_NT  , class Epi, class Sched>
; __device__ __forceinline__ void gemm_phase(LAS unsigned char* lds, const int tid_in, const int lda, const int ldb, const Sched& S, const Epi& E) {
;     ...
;         for (int t = 0; t < nt; t += 2) {
;             const bool last = (t == nt - 2);
;             const char* a1 = cA + (size_t)(t + 1) * kstep;
;             const char* a2 = last ? nA : cA + (size_t)(t + 2) * kstep; const char* b2 = last ? nB : cB + (size_t)(t + 2) * kstep;
;             const char* a3 = a2 + kstep; const char* b3 = b2 + kstep;
;             PG8_LDB(B0, 0, 0); PG8_LDB(B1, 0, 1); PG8_SCHED; PG8_LDA(At, 0, 0); PG8_STAGE(PG8_SA(1, 1), a1 + hstepA, voffA);
;             PG8_WAIT_V(8); PG8_WAIT_L(0); PG8_BAR; PG8_MMA(0, 0, At, B0); PG8_MMA(0, 1, At, B1); PG8_BAR; PG8_SCHED;
;             PG8_LDA(At, 0, 1); PG8_STAGE(PG8_SB(0, 0), b2, voffB); PG8_STAGE(PG8_SB(0, 1), b2 + hstepB, voffB); PG8_STAGE(PG8_SA(0, 0), a2, voffA);
.LBB0_689:
	v_add_u32_e32 v1, s35, v226
	ds_read_b128 v[132:135], v1
	ds_read_b128 v[136:139], v1 offset:1024
	ds_read_b128 v[140:143], v1 offset:2048
	ds_read_b128 v[144:147], v1 offset:3072
	v_add_u32_e32 v1, s44, v226
	ds_read_b128 v[148:151], v1
	ds_read_b128 v[152:155], v1 offset:1024
	ds_read_b128 v[156:159], v1 offset:2048
	ds_read_b128 v[160:163], v1 offset:3072
	s_add_i32 s68, s62, 2
	s_add_u32 s63, s60, 0xfffc0080
	s_addc_u32 s64, s61, -1
	s_cmp_eq_u32 s33, s62
	s_cselect_b32 s62, s31, s66
	s_cselect_b32 s65, s9, s64
	s_cselect_b32 s64, s14, s63
	s_cselect_b32 s63, s29, s67
	v_lshl_add_u64 v[2:3], s[60:61], 0, v[208:209]
	s_add_i32 m0, s70, 0xc000
	ds_read_b128 v[164:167], v231
	ds_read_b128 v[168:171], v231 offset:1024
	ds_read_b128 v[172:175], v231 offset:2048
	ds_read_b128 v[176:179], v231 offset:3072
	ds_read_b128 v[180:183], v231 offset:4096
	ds_read_b128 v[184:187], v231 offset:5120
	ds_read_b128 v[188:191], v231 offset:6144
	ds_read_b128 v[192:195], v231 offset:7168
	global_load_lds_dwordx4 v[2:3], off
	v_lshl_add_u64 v[2:3], s[60:61], 0, v[210:211]
	s_add_i32 m0, s70, 0xe000
	s_nop 0
	global_load_lds_dwordx4 v[2:3], off
	s_nop 0
	s_waitcnt vmcnt(8)
	s_waitcnt lgkmcnt(0)
	s_barrier
	s_setprio 1
	s_waitcnt lgkmcnt(0)
	v_mfma_f32_16x16x32_bf16 v[120:123], v[132:135], v[164:167], v[120:123]
	v_mfma_f32_16x16x32_bf16 v[120:123], v[136:139], v[168:171], v[120:123]
	v_mfma_f32_16x16x32_bf16 v[128:131], v[140:143], v[164:167], v[128:131]
	v_mfma_f32_16x16x32_bf16 v[128:131], v[144:147], v[168:171], v[128:131]
	v_mfma_f32_16x16x32_bf16 v[112:115], v[132:135], v[172:175], v[112:115]
	v_mfma_f32_16x16x32_bf16 v[112:115], v[136:139], v[176:179], v[112:115]
	v_mfma_f32_16x16x32_bf16 v[124:127], v[140:143], v[172:175], v[124:127]
	v_mfma_f32_16x16x32_bf16 v[124:127], v[144:147], v[176:179], v[124:127]
	v_mfma_f32_16x16x32_bf16 v[104:107], v[132:135], v[180:183], v[104:107]
	v_mfma_f32_16x16x32_bf16 v[104:107], v[136:139], v[184:187], v[104:107]
	v_mfma_f32_16x16x32_bf16 v[116:119], v[140:143], v[180:183], v[116:119]
	v_mfma_f32_16x16x32_bf16 v[116:119], v[144:147], v[184:187], v[116:119]
	v_mfma_f32_16x16x32_bf16 v[96:99], v[132:135], v[188:191], v[96:99]
	v_mfma_f32_16x16x32_bf16 v[96:99], v[136:139], v[192:195], v[96:99]
	v_mfma_f32_16x16x32_bf16 v[108:111], v[140:143], v[188:191], v[108:111]
	v_mfma_f32_16x16x32_bf16 v[108:111], v[144:147], v[192:195], v[108:111]
	s_setprio 0
	s_setprio 1
	v_mfma_f32_16x16x32_bf16 v[88:91], v[148:151], v[164:167], v[88:91]
	v_mfma_f32_16x16x32_bf16 v[88:91], v[152:155], v[168:171], v[88:91]
	v_mfma_f32_16x16x32_bf16 v[100:103], v[156:159], v[164:167], v[100:103]
	v_mfma_f32_16x16x32_bf16 v[100:103], v[160:163], v[168:171], v[100:103]
	v_mfma_f32_16x16x32_bf16 v[80:83], v[148:151], v[172:175], v[80:83]
	v_mfma_f32_16x16x32_bf16 v[80:83], v[152:155], v[176:179], v[80:83]
	v_mfma_f32_16x16x32_bf16 v[92:95], v[156:159], v[172:175], v[92:95]
	v_mfma_f32_16x16x32_bf16 v[92:95], v[160:163], v[176:179], v[92:95]
	v_mfma_f32_16x16x32_bf16 v[72:75], v[148:151], v[180:183], v[72:75]
	v_mfma_f32_16x16x32_bf16 v[72:75], v[152:155], v[184:187], v[72:75]
	v_mfma_f32_16x16x32_bf16 v[84:87], v[156:159], v[180:183], v[84:87]
	v_mfma_f32_16x16x32_bf16 v[84:87], v[160:163], v[184:187], v[84:87]
	v_mfma_f32_16x16x32_bf16 v[64:67], v[148:151], v[188:191], v[64:67]
	v_mfma_f32_16x16x32_bf16 v[64:67], v[152:155], v[192:195], v[64:67]
	v_mfma_f32_16x16x32_bf16 v[76:79], v[156:159], v[188:191], v[76:79]
	v_mfma_f32_16x16x32_bf16 v[76:79], v[160:163], v[192:195], v[76:79]
	s_setprio 0
	s_barrier
	s_add_i32 s69, s35, s45
	v_lshl_add_u64 v[196:197], s[62:63], 0, v[202:203]
	s_mov_b32 m0, s69
	ds_read_b128 v[164:167], v231 offset:16384
	ds_read_b128 v[168:171], v231 offset:17408
	ds_read_b128 v[172:175], v231 offset:18432
	ds_read_b128 v[176:179], v231 offset:19456
	ds_read_b128 v[180:183], v231 offset:20480
	ds_read_b128 v[184:187], v231 offset:21504
	ds_read_b128 v[188:191], v231 offset:22528
	ds_read_b128 v[192:195], v231 offset:23552
	global_load_lds_dwordx4 v[196:197], off
	s_add_i32 m0, s69, 0x2000
	s_add_u32 s92, s62, 0x40000
	v_lshl_add_u64 v[198:199], s[62:63], 0, v[206:207]
	s_addc_u32 s93, s63, 0
	s_add_i32 s69, s44, s45
	global_load_lds_dwordx4 v[198:199], off
	v_lshl_add_u64 v[2:3], s[92:93], 0, v[202:203]
	s_mov_b32 m0, s69
	v_lshl_add_u64 v[212:213], s[64:65], 0, v[200:201]
	global_load_lds_dwordx4 v[2:3], off
	v_lshl_add_u64 v[2:3], s[92:93], 0, v[206:207]
	s_add_i32 m0, s69, 0x2000
	v_lshl_add_u64 v[214:215], s[64:65], 0, v[204:205]
	global_load_lds_dwordx4 v[2:3], off
	s_mov_b32 m0, s70
	s_nop 0
	global_load_lds_dwordx4 v[212:213], off
	s_mov_b32 m0, s71
	s_nop 0
	global_load_lds_dwordx4 v[214:215], off
	s_waitcnt vmcnt(8)
	s_waitcnt lgkmcnt(0)
	s_barrier
; #define PG8_STAGE(bufoff, gbase, voff) do { _Pragma("unroll") for (int _i = 0; _i < 2; ++_i) \
;         __builtin_amdgcn_global_load_lds((const unsigned*)((const char*)(gbase) + (voff)[_i]), (LAS unsigned*)(lds + (bufoff) + ldsw + _i * 8192), 16, 0, 0); } while (0)
; #define PG8_LDA(dst, b, h) do { _Pragma("unroll") for (int m = 0; m < 4; ++m) _Pragma("unroll") for (int k = 0; k < 2; ++k) dst[m][k] = *(const LAS bf16x8*)(lds + PG8_SA(b, h) + aoff + m * 2048 + k * 1024); } while (0)
; #define PG8_LDB(dst, b, h) do { _Pragma("unroll") for (int n = 0; n < 2; ++n) _Pragma("unroll") for (int k = 0; k < 2; ++k) dst[n][k] = *(const LAS bf16x8*)(lds + PG8_SB(b, h) + boff + n * 2048 + k * 1024); } while (0)
; #define PG8_MMA(ai, bj, At, Bt) do { __builtin_amdgcn_s_setprio(1); _Pragma("unroll") for (int m = 0; m < 4; ++m) _Pragma("unroll") for (int n = 0; n < 2; ++n) _Pragma("unroll") for (int k = 0; k < 2; ++k) \
;         acc[ai][bj][m][n] = __builtin_amdgcn_mfma_f32_16x16x32_bf16(Bt[n][k], At[m][k], acc[ai][bj][m][n], 0, 0, 0); __builtin_amdgcn_s_setprio(0); } while (0)
; #define PG8_WAIT_V(n) asm volatile("s_waitcnt vmcnt(" #n ")" ::: "memory")
; #define PG8_WAIT_L(n) asm volatile("s_waitcnt lgkmcnt(" #n ")" ::: "memory")
; #define PG8_BAR __builtin_amdgcn_s_barrier()
; #define PG8_SCHED __builtin_amdgcn_sched_barrier(0)
; template <int FIXED_NT  , class Epi, class Sched>
; __device__ __forceinline__ void gemm_phase(LAS unsigned char* lds, const int tid_in, const int lda, const int ldb, const Sched& S, const Epi& E) {
;     ...
;             PG8_WAIT_V(8); PG8_WAIT_L(0); PG8_BAR; PG8_MMA(1, 0, At, B0); PG8_MMA(1, 1, At, B1); PG8_BAR; PG8_SCHED;
;             PG8_LDB(B0, 1, 0); PG8_LDB(B1, 1, 1); PG8_SCHED; PG8_LDA(At, 1, 0); PG8_STAGE(PG8_SA(0, 1), a2 + hstepA, voffA);
;             PG8_WAIT_V(8); PG8_WAIT_L(0); PG8_BAR; PG8_MMA(0, 0, At, B0); PG8_MMA(0, 1, At, B1); PG8_BAR; PG8_SCHED;
	s_setprio 1
	s_waitcnt lgkmcnt(0)
	v_mfma_f32_16x16x32_bf16 v[56:59], v[132:135], v[164:167], v[56:59]
	v_mfma_f32_16x16x32_bf16 v[56:59], v[136:139], v[168:171], v[56:59]
	v_mfma_f32_16x16x32_bf16 v[68:71], v[140:143], v[164:167], v[68:71]
	v_mfma_f32_16x16x32_bf16 v[68:71], v[144:147], v[168:171], v[68:71]
	v_mfma_f32_16x16x32_bf16 v[48:51], v[132:135], v[172:175], v[48:51]
	v_mfma_f32_16x16x32_bf16 v[48:51], v[136:139], v[176:179], v[48:51]
	v_mfma_f32_16x16x32_bf16 v[60:63], v[140:143], v[172:175], v[60:63]
	v_mfma_f32_16x16x32_bf16 v[60:63], v[144:147], v[176:179], v[60:63]
	v_mfma_f32_16x16x32_bf16 v[40:43], v[132:135], v[180:183], v[40:43]
	v_mfma_f32_16x16x32_bf16 v[40:43], v[136:139], v[184:187], v[40:43]
	v_mfma_f32_16x16x32_bf16 v[52:55], v[140:143], v[180:183], v[52:55]
	v_mfma_f32_16x16x32_bf16 v[52:55], v[144:147], v[184:187], v[52:55]
	v_mfma_f32_16x16x32_bf16 v[32:35], v[132:135], v[188:191], v[32:35]
	v_mfma_f32_16x16x32_bf16 v[32:35], v[136:139], v[192:195], v[32:35]
	v_mfma_f32_16x16x32_bf16 v[44:47], v[140:143], v[188:191], v[44:47]
	v_mfma_f32_16x16x32_bf16 v[44:47], v[144:147], v[192:195], v[44:47]
	s_setprio 0
	s_setprio 1
	v_mfma_f32_16x16x32_bf16 v[24:27], v[148:151], v[164:167], v[24:27]
	v_mfma_f32_16x16x32_bf16 v[24:27], v[152:155], v[168:171], v[24:27]
	v_mfma_f32_16x16x32_bf16 v[36:39], v[156:159], v[164:167], v[36:39]
	v_mfma_f32_16x16x32_bf16 v[36:39], v[160:163], v[168:171], v[36:39]
	v_mfma_f32_16x16x32_bf16 v[16:19], v[148:151], v[172:175], v[16:19]
	v_mfma_f32_16x16x32_bf16 v[16:19], v[152:155], v[176:179], v[16:19]
	v_mfma_f32_16x16x32_bf16 v[28:31], v[156:159], v[172:175], v[28:31]
	v_mfma_f32_16x16x32_bf16 v[28:31], v[160:163], v[176:179], v[28:31]
	v_mfma_f32_16x16x32_bf16 v[8:11], v[148:151], v[180:183], v[8:11]
	v_mfma_f32_16x16x32_bf16 v[8:11], v[152:155], v[184:187], v[8:11]
	v_mfma_f32_16x16x32_bf16 v[20:23], v[156:159], v[180:183], v[20:23]
	v_mfma_f32_16x16x32_bf16 v[20:23], v[160:163], v[184:187], v[20:23]
	v_mfma_f32_16x16x32_bf16 v[2:5], v[148:151], v[188:191], v[4:7]
	v_mfma_f32_16x16x32_bf16 v[2:5], v[152:155], v[192:195], v[2:5]
	v_mfma_f32_16x16x32_bf16 v[12:15], v[156:159], v[188:191], v[12:15]
	v_mfma_f32_16x16x32_bf16 v[12:15], v[160:163], v[192:195], v[12:15]
	s_setprio 0
	s_barrier
	s_add_i32 s69, 0, 0x18000
	v_add_u32_e32 v1, s69, v226
	s_add_i32 s79, 0, 0x1c000
	ds_read_b128 v[132:135], v1
	ds_read_b128 v[136:139], v1 offset:1024
	ds_read_b128 v[140:143], v1 offset:2048
	ds_read_b128 v[144:147], v1 offset:3072
	v_add_u32_e32 v1, s79, v226
	ds_read_b128 v[148:151], v1
	ds_read_b128 v[152:155], v1 offset:1024
	ds_read_b128 v[156:159], v1 offset:2048
	ds_read_b128 v[160:163], v1 offset:3072
	s_add_u32 s64, s64, 0x40000
	s_addc_u32 s65, s65, 0
	s_mov_b32 m0, s72
	v_lshl_add_u64 v[6:7], s[64:65], 0, v[200:201]
	ds_read_b128 v[164:167], v231 offset:32768
	ds_read_b128 v[168:171], v231 offset:33792
	ds_read_b128 v[172:175], v231 offset:34816
	ds_read_b128 v[176:179], v231 offset:35840
	ds_read_b128 v[180:183], v231 offset:36864
	ds_read_b128 v[184:187], v231 offset:37888
	ds_read_b128 v[188:191], v231 offset:38912
	ds_read_b128 v[192:195], v231 offset:39936
	global_load_lds_dwordx4 v[6:7], off
	v_lshl_add_u64 v[6:7], s[64:65], 0, v[204:205]
	s_mov_b32 m0, s73
	s_nop 0
	global_load_lds_dwordx4 v[6:7], off
	s_nop 0
	s_waitcnt vmcnt(8)
	s_waitcnt lgkmcnt(0)
	s_barrier
	s_setprio 1
	s_waitcnt lgkmcnt(0)
	v_mfma_f32_16x16x32_bf16 v[120:123], v[132:135], v[164:167], v[120:123]
	v_mfma_f32_16x16x32_bf16 v[120:123], v[136:139], v[168:171], v[120:123]
	v_mfma_f32_16x16x32_bf16 v[128:131], v[140:143], v[164:167], v[128:131]
	v_mfma_f32_16x16x32_bf16 v[128:131], v[144:147], v[168:171], v[128:131]
	v_mfma_f32_16x16x32_bf16 v[112:115], v[132:135], v[172:175], v[112:115]
	v_mfma_f32_16x16x32_bf16 v[112:115], v[136:139], v[176:179], v[112:115]
	v_mfma_f32_16x16x32_bf16 v[124:127], v[140:143], v[172:175], v[124:127]
	v_mfma_f32_16x16x32_bf16 v[124:127], v[144:147], v[176:179], v[124:127]
	v_mfma_f32_16x16x32_bf16 v[104:107], v[132:135], v[180:183], v[104:107]
	v_mfma_f32_16x16x32_bf16 v[104:107], v[136:139], v[184:187], v[104:107]
	v_mfma_f32_16x16x32_bf16 v[116:119], v[140:143], v[180:183], v[116:119]
	v_mfma_f32_16x16x32_bf16 v[116:119], v[144:147], v[184:187], v[116:119]
	v_mfma_f32_16x16x32_bf16 v[96:99], v[132:135], v[188:191], v[96:99]
	v_mfma_f32_16x16x32_bf16 v[96:99], v[136:139], v[192:195], v[96:99]
	v_mfma_f32_16x16x32_bf16 v[108:111], v[140:143], v[188:191], v[108:111]
	v_mfma_f32_16x16x32_bf16 v[108:111], v[144:147], v[192:195], v[108:111]
	s_setprio 0
	s_setprio 1
	v_mfma_f32_16x16x32_bf16 v[88:91], v[148:151], v[164:167], v[88:91]
	v_mfma_f32_16x16x32_bf16 v[88:91], v[152:155], v[168:171], v[88:91]
	v_mfma_f32_16x16x32_bf16 v[100:103], v[156:159], v[164:167], v[100:103]
	v_mfma_f32_16x16x32_bf16 v[100:103], v[160:163], v[168:171], v[100:103]
	v_mfma_f32_16x16x32_bf16 v[80:83], v[148:151], v[172:175], v[80:83]
	v_mfma_f32_16x16x32_bf16 v[80:83], v[152:155], v[176:179], v[80:83]
	v_mfma_f32_16x16x32_bf16 v[92:95], v[156:159], v[172:175], v[92:95]
	v_mfma_f32_16x16x32_bf16 v[92:95], v[160:163], v[176:179], v[92:95]
	v_mfma_f32_16x16x32_bf16 v[72:75], v[148:151], v[180:183], v[72:75]
	v_mfma_f32_16x16x32_bf16 v[72:75], v[152:155], v[184:187], v[72:75]
	v_mfma_f32_16x16x32_bf16 v[84:87], v[156:159], v[180:183], v[84:87]
	v_mfma_f32_16x16x32_bf16 v[84:87], v[160:163], v[184:187], v[84:87]
	v_mfma_f32_16x16x32_bf16 v[64:67], v[148:151], v[188:191], v[64:67]
	v_mfma_f32_16x16x32_bf16 v[64:67], v[152:155], v[192:195], v[64:67]
	v_mfma_f32_16x16x32_bf16 v[76:79], v[156:159], v[188:191], v[76:79]
	v_mfma_f32_16x16x32_bf16 v[76:79], v[160:163], v[192:195], v[76:79]
	s_setprio 0
	s_barrier
; #define PG8_STAGE(bufoff, gbase, voff) do { _Pragma("unroll") for (int _i = 0; _i < 2; ++_i) \
;         __builtin_amdgcn_global_load_lds((const unsigned*)((const char*)(gbase) + (voff)[_i]), (LAS unsigned*)(lds + (bufoff) + ldsw + _i * 8192), 16, 0, 0); } while (0)
; #define PG8_LDA(dst, b, h) do { _Pragma("unroll") for (int m = 0; m < 4; ++m) _Pragma("unroll") for (int k = 0; k < 2; ++k) dst[m][k] = *(const LAS bf16x8*)(lds + PG8_SA(b, h) + aoff + m * 2048 + k * 1024); } while (0)
; #define PG8_MMA(ai, bj, At, Bt) do { __builtin_amdgcn_s_setprio(1); _Pragma("unroll") for (int m = 0; m < 4; ++m) _Pragma("unroll") for (int n = 0; n < 2; ++n) _Pragma("unroll") for (int k = 0; k < 2; ++k) \
;         acc[ai][bj][m][n] = __builtin_amdgcn_mfma_f32_16x16x32_bf16(Bt[n][k], At[m][k], acc[ai][bj][m][n], 0, 0, 0); __builtin_amdgcn_s_setprio(0); } while (0)
; #define PG8_WAIT_V(n) asm volatile("s_waitcnt vmcnt(" #n ")" ::: "memory")
; #define PG8_WAIT_L(n) asm volatile("s_waitcnt lgkmcnt(" #n ")" ::: "memory")
; #define PG8_BAR __builtin_amdgcn_s_barrier()
; #define PG8_SCHED __builtin_amdgcn_sched_barrier(0)
; template <int FIXED_NT  , class Epi, class Sched>
; __device__ __forceinline__ void gemm_phase(LAS unsigned char* lds, const int tid_in, const int lda, const int ldb, const Sched& S, const Epi& E) {
;     ...
;             PG8_LDA(At, 1, 1); PG8_STAGE(PG8_SB(1, 0), b3, voffB); PG8_STAGE(PG8_SB(1, 1), b3 + hstepB, voffB); PG8_STAGE(PG8_SA(1, 0), a3, voffA);
;             PG8_WAIT_V(8); PG8_WAIT_L(0); PG8_BAR; PG8_MMA(1, 0, At, B0); PG8_MMA(1, 1, At, B1); PG8_BAR; PG8_SCHED;
;         }
	s_add_i32 s64, s69, s45
	v_lshl_add_u64 v[6:7], v[196:197], 0, s[18:19]
	s_mov_b32 m0, s64
	ds_read_b128 v[164:167], v231 offset:49152
	ds_read_b128 v[168:171], v231 offset:50176
	ds_read_b128 v[172:175], v231 offset:51200
	ds_read_b128 v[176:179], v231 offset:52224
	ds_read_b128 v[180:183], v231 offset:53248
	ds_read_b128 v[184:187], v231 offset:54272
	ds_read_b128 v[188:191], v231 offset:55296
	ds_read_b128 v[192:195], v231 offset:56320
	global_load_lds_dwordx4 v[6:7], off
	s_add_i32 m0, s64, 0x2000
	s_add_u32 s62, s62, 0x40080
	v_lshl_add_u64 v[6:7], v[198:199], 0, s[18:19]
	s_addc_u32 s63, s63, 0
	s_add_i32 s64, s79, s45
	global_load_lds_dwordx4 v[6:7], off
	v_lshl_add_u64 v[6:7], s[62:63], 0, v[202:203]
	s_mov_b32 m0, s64
	s_nop 0
	global_load_lds_dwordx4 v[6:7], off
	v_lshl_add_u64 v[6:7], s[62:63], 0, v[206:207]
	s_add_i32 m0, s64, 0x2000
	s_nop 0
	global_load_lds_dwordx4 v[6:7], off
	v_lshl_add_u64 v[6:7], v[212:213], 0, s[18:19]
	s_mov_b32 m0, s76
	s_nop 0
	global_load_lds_dwordx4 v[6:7], off
	v_lshl_add_u64 v[6:7], v[214:215], 0, s[18:19]
	s_mov_b32 m0, s85
	s_nop 0
	global_load_lds_dwordx4 v[6:7], off
	s_waitcnt vmcnt(8)
	s_waitcnt lgkmcnt(0)
	s_barrier
	s_setprio 1
	s_waitcnt lgkmcnt(0)
	v_mfma_f32_16x16x32_bf16 v[56:59], v[132:135], v[164:167], v[56:59]
	v_mfma_f32_16x16x32_bf16 v[56:59], v[136:139], v[168:171], v[56:59]
	v_mfma_f32_16x16x32_bf16 v[68:71], v[140:143], v[164:167], v[68:71]
	v_mfma_f32_16x16x32_bf16 v[68:71], v[144:147], v[168:171], v[68:71]
	v_mfma_f32_16x16x32_bf16 v[48:51], v[132:135], v[172:175], v[48:51]
	v_mfma_f32_16x16x32_bf16 v[48:51], v[136:139], v[176:179], v[48:51]
	v_mfma_f32_16x16x32_bf16 v[60:63], v[140:143], v[172:175], v[60:63]
	v_mfma_f32_16x16x32_bf16 v[60:63], v[144:147], v[176:179], v[60:63]
	v_mfma_f32_16x16x32_bf16 v[40:43], v[132:135], v[180:183], v[40:43]
	v_mfma_f32_16x16x32_bf16 v[40:43], v[136:139], v[184:187], v[40:43]
	v_mfma_f32_16x16x32_bf16 v[52:55], v[140:143], v[180:183], v[52:55]
	v_mfma_f32_16x16x32_bf16 v[52:55], v[144:147], v[184:187], v[52:55]
	v_mfma_f32_16x16x32_bf16 v[32:35], v[132:135], v[188:191], v[32:35]
	v_mfma_f32_16x16x32_bf16 v[32:35], v[136:139], v[192:195], v[32:35]
	v_mfma_f32_16x16x32_bf16 v[44:47], v[140:143], v[188:191], v[44:47]
	v_mfma_f32_16x16x32_bf16 v[44:47], v[144:147], v[192:195], v[44:47]
	s_setprio 0
	s_setprio 1
	v_mfma_f32_16x16x32_bf16 v[24:27], v[148:151], v[164:167], v[24:27]
	v_mfma_f32_16x16x32_bf16 v[24:27], v[152:155], v[168:171], v[24:27]
	v_mfma_f32_16x16x32_bf16 v[36:39], v[156:159], v[164:167], v[36:39]
	v_mfma_f32_16x16x32_bf16 v[36:39], v[160:163], v[168:171], v[36:39]
	v_mfma_f32_16x16x32_bf16 v[16:19], v[148:151], v[172:175], v[16:19]
	v_mfma_f32_16x16x32_bf16 v[16:19], v[152:155], v[176:179], v[16:19]
	v_mfma_f32_16x16x32_bf16 v[28:31], v[156:159], v[172:175], v[28:31]
	v_mfma_f32_16x16x32_bf16 v[28:31], v[160:163], v[176:179], v[28:31]
	v_mfma_f32_16x16x32_bf16 v[6:9], v[148:151], v[180:183], v[8:11]
	v_mfma_f32_16x16x32_bf16 v[8:11], v[152:155], v[184:187], v[6:9]
	v_mfma_f32_16x16x32_bf16 v[20:23], v[156:159], v[180:183], v[20:23]
	v_mfma_f32_16x16x32_bf16 v[20:23], v[160:163], v[184:187], v[20:23]
	v_mfma_f32_16x16x32_bf16 v[2:5], v[148:151], v[188:191], v[2:5]
	v_mfma_f32_16x16x32_bf16 v[4:7], v[152:155], v[192:195], v[2:5]
	v_mfma_f32_16x16x32_bf16 v[12:15], v[156:159], v[188:191], v[12:15]
	v_mfma_f32_16x16x32_bf16 v[12:15], v[160:163], v[192:195], v[12:15]
	s_setprio 0
	s_barrier
	s_add_u32 s60, s60, 0x100
	s_addc_u32 s61, s61, 0
	s_add_u32 s66, s66, 0x100
	s_addc_u32 s67, s67, 0
	s_cmp_ge_i32 s68, s7
	s_mov_b32 s62, s68
	s_cbranch_scc0 .LBB0_689

; #define PG8_STAGE(bufoff, gbase, voff) do { _Pragma("unroll") for (int _i = 0; _i < 2; ++_i) \
;         __builtin_amdgcn_global_load_lds((const unsigned*)((const char*)(gbase) + (voff)[_i]), (LAS unsigned*)(lds + (bufoff) + ldsw + _i * 8192), 16, 0, 0); } while (0)
; #define PG8_LDA(dst, b, h) do { _Pragma("unroll") for (int m = 0; m < 4; ++m) _Pragma("unroll") for (int k = 0; k < 2; ++k) dst[m][k] = *(const LAS bf16x8*)(lds + PG8_SA(b, h) + aoff + m * 2048 + k * 1024); } while (0)
; #define PG8_LDB(dst, b, h) do { _Pragma("unroll") for (int n = 0; n < 2; ++n) _Pragma("unroll") for (int k = 0; k < 2; ++k) dst[n][k] = *(const LAS bf16x8*)(lds + PG8_SB(b, h) + boff + n * 2048 + k * 1024); } while (0)
; #define PG8_MMA(ai, bj, At, Bt) do { __builtin_amdgcn_s_setprio(1); _Pragma("unroll") for (int m = 0; m < 4; ++m) _Pragma("unroll") for (int n = 0; n < 2; ++n) _Pragma("unroll") for (int k = 0; k < 2; ++k) \
;         acc[ai][bj][m][n] = __builtin_amdgcn_mfma_f32_16x16x32_bf16(Bt[n][k], At[m][k], acc[ai][bj][m][n], 0, 0, 0); __builtin_amdgcn_s_setprio(0); } while (0)
; #define PG8_WAIT_V(n) asm volatile("s_waitcnt vmcnt(" #n ")" ::: "memory")
; #define PG8_WAIT_L(n) asm volatile("s_waitcnt lgkmcnt(" #n ")" ::: "memory")
; #define PG8_BAR __builtin_amdgcn_s_barrier()
; #define PG8_SCHED __builtin_amdgcn_sched_barrier(0)
; template <int FIXED_NT  , class Epi, class Sched>
; __device__ __forceinline__ void gemm_phase(LAS unsigned char* lds, const int tid_in, const int lda, const int ldb, const Sched& S, const Epi& E) {
;     ...
;         for (int t = 0; t < nt; t += 2) {
;             const bool last = (t == nt - 2);
;             const char* a1 = cA + (size_t)(t + 1) * kstep;
;             const char* a2 = last ? nA : cA + (size_t)(t + 2) * kstep; const char* b2 = last ? nB : cB + (size_t)(t + 2) * kstep;
;             const char* a3 = a2 + kstep; const char* b3 = b2 + kstep;
;             PG8_LDB(B0, 0, 0); PG8_LDB(B1, 0, 1); PG8_SCHED; PG8_LDA(At, 0, 0); PG8_STAGE(PG8_SA(1, 1), a1 + hstepA, voffA);
;             PG8_WAIT_V(8); PG8_WAIT_L(0); PG8_BAR; PG8_MMA(0, 0, At, B0); PG8_MMA(0, 1, At, B1); PG8_BAR; PG8_SCHED;
;             PG8_LDA(At, 0, 1); PG8_STAGE(PG8_SB(0, 0), b2, voffB); PG8_STAGE(PG8_SB(0, 1), b2 + hstepB, voffB); PG8_STAGE(PG8_SA(0, 0), a2, voffA);
.LBB0_1026:
	s_waitcnt lgkmcnt(0)
	ds_read_b128 v[128:131], v214
	ds_read_b128 v[132:135], v214 offset:1024
	ds_read_b128 v[136:139], v214 offset:2048
	ds_read_b128 v[140:143], v214 offset:3072
	ds_read_b128 v[144:147], v215
	ds_read_b128 v[148:151], v215 offset:1024
	ds_read_b128 v[152:155], v215 offset:2048
	ds_read_b128 v[156:159], v215 offset:3072
	s_add_i32 s80, s62, 2
	s_add_u32 s63, s60, 0xfff80080
	s_addc_u32 s64, s61, -1
	s_cmp_eq_u32 s86, s62
	s_cselect_b32 s62, s85, s88
	s_cselect_b32 s65, s16, s64
	s_cselect_b32 s64, s59, s63
	s_cselect_b32 s63, s79, s89
	v_lshl_add_u64 v[204:205], s[60:61], 0, v[188:189]
	s_add_i32 m0, s44, 0xc000
	ds_read_b128 v[160:163], v216
	ds_read_b128 v[164:167], v216 offset:1024
	ds_read_b128 v[168:171], v216 offset:2048
	ds_read_b128 v[172:175], v216 offset:3072
	ds_read_b128 v[192:195], v216 offset:4096
	ds_read_b128 v[196:199], v216 offset:5120
	ds_read_b128 v[200:203], v216 offset:6144
	ds_read_b128 v[218:221], v216 offset:7168
	global_load_lds_dwordx4 v[204:205], off
	v_lshl_add_u64 v[204:205], s[60:61], 0, v[190:191]
	s_add_i32 m0, s44, 0xe000
	s_nop 0
	global_load_lds_dwordx4 v[204:205], off
	s_nop 0
	s_waitcnt vmcnt(8)
	s_waitcnt lgkmcnt(0)
	s_barrier
	s_setprio 1
	s_waitcnt lgkmcnt(0)
	v_mfma_f32_16x16x32_bf16 v[124:127], v[128:131], v[160:163], v[124:127]
	v_mfma_f32_16x16x32_bf16 v[124:127], v[132:135], v[164:167], v[124:127]
	v_mfma_f32_16x16x32_bf16 v[120:123], v[136:139], v[160:163], v[120:123]
	v_mfma_f32_16x16x32_bf16 v[120:123], v[140:143], v[164:167], v[120:123]
	v_mfma_f32_16x16x32_bf16 v[108:111], v[128:131], v[168:171], v[108:111]
	v_mfma_f32_16x16x32_bf16 v[108:111], v[132:135], v[172:175], v[108:111]
	v_mfma_f32_16x16x32_bf16 v[104:107], v[136:139], v[168:171], v[104:107]
	v_mfma_f32_16x16x32_bf16 v[104:107], v[140:143], v[172:175], v[104:107]
	v_mfma_f32_16x16x32_bf16 v[92:95], v[128:131], v[192:195], v[92:95]
	v_mfma_f32_16x16x32_bf16 v[92:95], v[132:135], v[196:199], v[92:95]
	v_mfma_f32_16x16x32_bf16 v[88:91], v[136:139], v[192:195], v[88:91]
	v_mfma_f32_16x16x32_bf16 v[88:91], v[140:143], v[196:199], v[88:91]
	v_mfma_f32_16x16x32_bf16 v[76:79], v[128:131], v[200:203], v[76:79]
	v_mfma_f32_16x16x32_bf16 v[76:79], v[132:135], v[218:221], v[76:79]
	v_mfma_f32_16x16x32_bf16 v[72:75], v[136:139], v[200:203], v[72:75]
	v_mfma_f32_16x16x32_bf16 v[72:75], v[140:143], v[218:221], v[72:75]
	s_setprio 0
	s_setprio 1
	v_mfma_f32_16x16x32_bf16 v[116:119], v[144:147], v[160:163], v[116:119]
	v_mfma_f32_16x16x32_bf16 v[116:119], v[148:151], v[164:167], v[116:119]
	v_mfma_f32_16x16x32_bf16 v[112:115], v[152:155], v[160:163], v[112:115]
	v_mfma_f32_16x16x32_bf16 v[112:115], v[156:159], v[164:167], v[112:115]
	v_mfma_f32_16x16x32_bf16 v[100:103], v[144:147], v[168:171], v[100:103]
	v_mfma_f32_16x16x32_bf16 v[100:103], v[148:151], v[172:175], v[100:103]
	v_mfma_f32_16x16x32_bf16 v[96:99], v[152:155], v[168:171], v[96:99]
	v_mfma_f32_16x16x32_bf16 v[96:99], v[156:159], v[172:175], v[96:99]
	v_mfma_f32_16x16x32_bf16 v[84:87], v[144:147], v[192:195], v[84:87]
	v_mfma_f32_16x16x32_bf16 v[84:87], v[148:151], v[196:199], v[84:87]
	v_mfma_f32_16x16x32_bf16 v[80:83], v[152:155], v[192:195], v[80:83]
	v_mfma_f32_16x16x32_bf16 v[80:83], v[156:159], v[196:199], v[80:83]
	v_mfma_f32_16x16x32_bf16 v[68:71], v[144:147], v[200:203], v[68:71]
	v_mfma_f32_16x16x32_bf16 v[68:71], v[148:151], v[218:221], v[68:71]
	v_mfma_f32_16x16x32_bf16 v[64:67], v[152:155], v[200:203], v[64:67]
	v_mfma_f32_16x16x32_bf16 v[64:67], v[156:159], v[218:221], v[64:67]
	s_setprio 0
	s_barrier
	s_add_i32 s90, s72, s35
	v_lshl_add_u64 v[204:205], s[62:63], 0, v[178:179]
	s_mov_b32 m0, s90
	ds_read_b128 v[160:163], v216 offset:16384
	ds_read_b128 v[164:167], v216 offset:17408
	ds_read_b128 v[168:171], v216 offset:18432
	ds_read_b128 v[172:175], v216 offset:19456
	ds_read_b128 v[192:195], v216 offset:20480
	ds_read_b128 v[196:199], v216 offset:21504
	ds_read_b128 v[200:203], v216 offset:22528
	ds_read_b128 v[218:221], v216 offset:23552
	global_load_lds_dwordx4 v[204:205], off
	s_add_i32 m0, s90, 0x2000
	s_add_u32 s90, s62, 0x80000
	v_lshl_add_u64 v[222:223], s[62:63], 0, v[182:183]
	s_addc_u32 s91, s63, 0
	s_add_i32 s92, s73, s35
	global_load_lds_dwordx4 v[222:223], off
	v_lshl_add_u64 v[226:227], s[90:91], 0, v[178:179]
	s_mov_b32 m0, s92
	v_lshl_add_u64 v[228:229], s[64:65], 0, v[180:181]
	global_load_lds_dwordx4 v[226:227], off
	v_lshl_add_u64 v[226:227], s[90:91], 0, v[182:183]
	s_add_i32 m0, s92, 0x2000
	s_nop 0
	global_load_lds_dwordx4 v[226:227], off
	v_lshl_add_u64 v[226:227], s[64:65], 0, v[176:177]
	s_mov_b32 m0, s44
	s_nop 0
	global_load_lds_dwordx4 v[226:227], off
	s_mov_b32 m0, s45
	s_nop 0
	global_load_lds_dwordx4 v[228:229], off
	s_nop 0
	s_waitcnt vmcnt(8)
	s_waitcnt lgkmcnt(0)
	s_barrier
; #define PG8_STAGE(bufoff, gbase, voff) do { _Pragma("unroll") for (int _i = 0; _i < 2; ++_i) \
;         __builtin_amdgcn_global_load_lds((const unsigned*)((const char*)(gbase) + (voff)[_i]), (LAS unsigned*)(lds + (bufoff) + ldsw + _i * 8192), 16, 0, 0); } while (0)
; #define PG8_LDA(dst, b, h) do { _Pragma("unroll") for (int m = 0; m < 4; ++m) _Pragma("unroll") for (int k = 0; k < 2; ++k) dst[m][k] = *(const LAS bf16x8*)(lds + PG8_SA(b, h) + aoff + m * 2048 + k * 1024); } while (0)
; #define PG8_LDB(dst, b, h) do { _Pragma("unroll") for (int n = 0; n < 2; ++n) _Pragma("unroll") for (int k = 0; k < 2; ++k) dst[n][k] = *(const LAS bf16x8*)(lds + PG8_SB(b, h) + boff + n * 2048 + k * 1024); } while (0)
; #define PG8_MMA(ai, bj, At, Bt) do { __builtin_amdgcn_s_setprio(1); _Pragma("unroll") for (int m = 0; m < 4; ++m) _Pragma("unroll") for (int n = 0; n < 2; ++n) _Pragma("unroll") for (int k = 0; k < 2; ++k) \
;         acc[ai][bj][m][n] = __builtin_amdgcn_mfma_f32_16x16x32_bf16(Bt[n][k], At[m][k], acc[ai][bj][m][n], 0, 0, 0); __builtin_amdgcn_s_setprio(0); } while (0)
; #define PG8_WAIT_V(n) asm volatile("s_waitcnt vmcnt(" #n ")" ::: "memory")
; #define PG8_WAIT_L(n) asm volatile("s_waitcnt lgkmcnt(" #n ")" ::: "memory")
; #define PG8_BAR __builtin_amdgcn_s_barrier()
; #define PG8_SCHED __builtin_amdgcn_sched_barrier(0)
; template <int FIXED_NT  , class Epi, class Sched>
; __device__ __forceinline__ void gemm_phase(LAS unsigned char* lds, const int tid_in, const int lda, const int ldb, const Sched& S, const Epi& E) {
;     ...
;             PG8_WAIT_V(8); PG8_WAIT_L(0); PG8_BAR; PG8_MMA(1, 0, At, B0); PG8_MMA(1, 1, At, B1); PG8_BAR; PG8_SCHED;
;             PG8_LDB(B0, 1, 0); PG8_LDB(B1, 1, 1); PG8_SCHED; PG8_LDA(At, 1, 0); PG8_STAGE(PG8_SA(0, 1), a2 + hstepA, voffA);
;             PG8_WAIT_V(8); PG8_WAIT_L(0); PG8_BAR; PG8_MMA(0, 0, At, B0); PG8_MMA(0, 1, At, B1); PG8_BAR; PG8_SCHED;
	s_setprio 1
	s_waitcnt lgkmcnt(0)
	v_mfma_f32_16x16x32_bf16 v[60:63], v[128:131], v[160:163], v[60:63]
	v_mfma_f32_16x16x32_bf16 v[60:63], v[132:135], v[164:167], v[60:63]
	v_mfma_f32_16x16x32_bf16 v[56:59], v[136:139], v[160:163], v[56:59]
	v_mfma_f32_16x16x32_bf16 v[56:59], v[140:143], v[164:167], v[56:59]
	v_mfma_f32_16x16x32_bf16 v[44:47], v[128:131], v[168:171], v[44:47]
	v_mfma_f32_16x16x32_bf16 v[44:47], v[132:135], v[172:175], v[44:47]
	v_mfma_f32_16x16x32_bf16 v[40:43], v[136:139], v[168:171], v[40:43]
	v_mfma_f32_16x16x32_bf16 v[40:43], v[140:143], v[172:175], v[40:43]
	v_mfma_f32_16x16x32_bf16 v[28:31], v[128:131], v[192:195], v[28:31]
	v_mfma_f32_16x16x32_bf16 v[28:31], v[132:135], v[196:199], v[28:31]
	v_mfma_f32_16x16x32_bf16 v[24:27], v[136:139], v[192:195], v[24:27]
	v_mfma_f32_16x16x32_bf16 v[24:27], v[140:143], v[196:199], v[24:27]
	v_mfma_f32_16x16x32_bf16 v[12:15], v[128:131], v[200:203], v[12:15]
	v_mfma_f32_16x16x32_bf16 v[12:15], v[132:135], v[218:221], v[12:15]
	v_mfma_f32_16x16x32_bf16 v[8:11], v[136:139], v[200:203], v[8:11]
	v_mfma_f32_16x16x32_bf16 v[8:11], v[140:143], v[218:221], v[8:11]
	s_setprio 0
	s_setprio 1
	v_mfma_f32_16x16x32_bf16 v[52:55], v[144:147], v[160:163], v[52:55]
	v_mfma_f32_16x16x32_bf16 v[52:55], v[148:151], v[164:167], v[52:55]
	v_mfma_f32_16x16x32_bf16 v[48:51], v[152:155], v[160:163], v[48:51]
	v_mfma_f32_16x16x32_bf16 v[48:51], v[156:159], v[164:167], v[48:51]
	v_mfma_f32_16x16x32_bf16 v[36:39], v[144:147], v[168:171], v[36:39]
	v_mfma_f32_16x16x32_bf16 v[36:39], v[148:151], v[172:175], v[36:39]
	v_mfma_f32_16x16x32_bf16 v[32:35], v[152:155], v[168:171], v[32:35]
	v_mfma_f32_16x16x32_bf16 v[32:35], v[156:159], v[172:175], v[32:35]
	v_mfma_f32_16x16x32_bf16 v[20:23], v[144:147], v[192:195], v[20:23]
	v_mfma_f32_16x16x32_bf16 v[20:23], v[148:151], v[196:199], v[20:23]
	v_mfma_f32_16x16x32_bf16 v[16:19], v[152:155], v[192:195], v[16:19]
	v_mfma_f32_16x16x32_bf16 v[16:19], v[156:159], v[196:199], v[16:19]
	v_mfma_f32_16x16x32_bf16 v[4:7], v[144:147], v[200:203], v[4:7]
	v_mfma_f32_16x16x32_bf16 v[4:7], v[148:151], v[218:221], v[4:7]
	v_mfma_f32_16x16x32_bf16 v[0:3], v[152:155], v[200:203], v[0:3]
	v_mfma_f32_16x16x32_bf16 v[0:3], v[156:159], v[218:221], v[0:3]
	s_setprio 0
	s_barrier
	s_add_i32 s90, 0, 0x18000
	s_add_i32 s91, 0, 0x1c000
	v_add_u32_e32 v140, s90, v206
	v_add_u32_e32 v156, s91, v206
	ds_read_b128 v[128:131], v140
	ds_read_b128 v[132:135], v140 offset:1024
	ds_read_b128 v[136:139], v140 offset:2048
	ds_read_b128 v[140:143], v140 offset:3072
	ds_read_b128 v[144:147], v156
	ds_read_b128 v[148:151], v156 offset:1024
	ds_read_b128 v[152:155], v156 offset:2048
	ds_read_b128 v[156:159], v156 offset:3072
	s_add_u32 s64, s64, 0x80000
	s_addc_u32 s65, s65, 0
	s_mov_b32 m0, s66
	v_lshl_add_u64 v[230:231], s[64:65], 0, v[176:177]
	ds_read_b128 v[160:163], v216 offset:32768
	ds_read_b128 v[164:167], v216 offset:33792
	ds_read_b128 v[168:171], v216 offset:34816
	ds_read_b128 v[172:175], v216 offset:35840
	ds_read_b128 v[192:195], v216 offset:36864
	ds_read_b128 v[196:199], v216 offset:37888
	ds_read_b128 v[200:203], v216 offset:38912
	ds_read_b128 v[218:221], v216 offset:39936
	global_load_lds_dwordx4 v[230:231], off
	v_lshl_add_u64 v[230:231], s[64:65], 0, v[180:181]
	s_mov_b32 m0, s67
	s_nop 0
	global_load_lds_dwordx4 v[230:231], off
	s_nop 0
	s_waitcnt vmcnt(8)
	s_waitcnt lgkmcnt(0)
	s_barrier
	s_setprio 1
	s_waitcnt lgkmcnt(0)
	v_mfma_f32_16x16x32_bf16 v[124:127], v[128:131], v[160:163], v[124:127]
	v_mfma_f32_16x16x32_bf16 v[124:127], v[132:135], v[164:167], v[124:127]
	v_mfma_f32_16x16x32_bf16 v[120:123], v[136:139], v[160:163], v[120:123]
	v_mfma_f32_16x16x32_bf16 v[120:123], v[140:143], v[164:167], v[120:123]
	v_mfma_f32_16x16x32_bf16 v[108:111], v[128:131], v[168:171], v[108:111]
	v_mfma_f32_16x16x32_bf16 v[108:111], v[132:135], v[172:175], v[108:111]
	v_mfma_f32_16x16x32_bf16 v[104:107], v[136:139], v[168:171], v[104:107]
	v_mfma_f32_16x16x32_bf16 v[104:107], v[140:143], v[172:175], v[104:107]
	v_mfma_f32_16x16x32_bf16 v[92:95], v[128:131], v[192:195], v[92:95]
	v_mfma_f32_16x16x32_bf16 v[92:95], v[132:135], v[196:199], v[92:95]
	v_mfma_f32_16x16x32_bf16 v[88:91], v[136:139], v[192:195], v[88:91]
	v_mfma_f32_16x16x32_bf16 v[88:91], v[140:143], v[196:199], v[88:91]
	v_mfma_f32_16x16x32_bf16 v[76:79], v[128:131], v[200:203], v[76:79]
	v_mfma_f32_16x16x32_bf16 v[76:79], v[132:135], v[218:221], v[76:79]
	v_mfma_f32_16x16x32_bf16 v[72:75], v[136:139], v[200:203], v[72:75]
	v_mfma_f32_16x16x32_bf16 v[72:75], v[140:143], v[218:221], v[72:75]
	s_setprio 0
	s_setprio 1
	v_mfma_f32_16x16x32_bf16 v[116:119], v[144:147], v[160:163], v[116:119]
	v_mfma_f32_16x16x32_bf16 v[116:119], v[148:151], v[164:167], v[116:119]
	v_mfma_f32_16x16x32_bf16 v[112:115], v[152:155], v[160:163], v[112:115]
	v_mfma_f32_16x16x32_bf16 v[112:115], v[156:159], v[164:167], v[112:115]
	v_mfma_f32_16x16x32_bf16 v[100:103], v[144:147], v[168:171], v[100:103]
	v_mfma_f32_16x16x32_bf16 v[100:103], v[148:151], v[172:175], v[100:103]
	v_mfma_f32_16x16x32_bf16 v[96:99], v[152:155], v[168:171], v[96:99]
	v_mfma_f32_16x16x32_bf16 v[96:99], v[156:159], v[172:175], v[96:99]
	v_mfma_f32_16x16x32_bf16 v[84:87], v[144:147], v[192:195], v[84:87]
	v_mfma_f32_16x16x32_bf16 v[84:87], v[148:151], v[196:199], v[84:87]
	v_mfma_f32_16x16x32_bf16 v[80:83], v[152:155], v[192:195], v[80:83]
	v_mfma_f32_16x16x32_bf16 v[80:83], v[156:159], v[196:199], v[80:83]
	v_mfma_f32_16x16x32_bf16 v[68:71], v[144:147], v[200:203], v[68:71]
	v_mfma_f32_16x16x32_bf16 v[68:71], v[148:151], v[218:221], v[68:71]
	v_mfma_f32_16x16x32_bf16 v[64:67], v[152:155], v[200:203], v[64:67]
	v_mfma_f32_16x16x32_bf16 v[64:67], v[156:159], v[218:221], v[64:67]
	s_setprio 0
	s_barrier
; #define PG8_STAGE(bufoff, gbase, voff) do { _Pragma("unroll") for (int _i = 0; _i < 2; ++_i) \
;         __builtin_amdgcn_global_load_lds((const unsigned*)((const char*)(gbase) + (voff)[_i]), (LAS unsigned*)(lds + (bufoff) + ldsw + _i * 8192), 16, 0, 0); } while (0)
; #define PG8_LDA(dst, b, h) do { _Pragma("unroll") for (int m = 0; m < 4; ++m) _Pragma("unroll") for (int k = 0; k < 2; ++k) dst[m][k] = *(const LAS bf16x8*)(lds + PG8_SA(b, h) + aoff + m * 2048 + k * 1024); } while (0)
; #define PG8_MMA(ai, bj, At, Bt) do { __builtin_amdgcn_s_setprio(1); _Pragma("unroll") for (int m = 0; m < 4; ++m) _Pragma("unroll") for (int n = 0; n < 2; ++n) _Pragma("unroll") for (int k = 0; k < 2; ++k) \
;         acc[ai][bj][m][n] = __builtin_amdgcn_mfma_f32_16x16x32_bf16(Bt[n][k], At[m][k], acc[ai][bj][m][n], 0, 0, 0); __builtin_amdgcn_s_setprio(0); } while (0)
; #define PG8_WAIT_V(n) asm volatile("s_waitcnt vmcnt(" #n ")" ::: "memory")
; #define PG8_WAIT_L(n) asm volatile("s_waitcnt lgkmcnt(" #n ")" ::: "memory")
; #define PG8_BAR __builtin_amdgcn_s_barrier()
; #define PG8_SCHED __builtin_amdgcn_sched_barrier(0)
; template <int FIXED_NT  , class Epi, class Sched>
; __device__ __forceinline__ void gemm_phase(LAS unsigned char* lds, const int tid_in, const int lda, const int ldb, const Sched& S, const Epi& E) {
;     ...
;             PG8_LDA(At, 1, 1); PG8_STAGE(PG8_SB(1, 0), b3, voffB); PG8_STAGE(PG8_SB(1, 1), b3 + hstepB, voffB); PG8_STAGE(PG8_SA(1, 0), a3, voffA);
;             PG8_WAIT_V(8); PG8_WAIT_L(0); PG8_BAR; PG8_MMA(1, 0, At, B0); PG8_MMA(1, 1, At, B1); PG8_BAR; PG8_SCHED;
;         }
	s_add_i32 s64, s90, s35
	v_lshl_add_u64 v[204:205], v[204:205], 0, s[22:23]
	s_mov_b32 m0, s64
	ds_read_b128 v[160:163], v216 offset:49152
	ds_read_b128 v[164:167], v216 offset:50176
	ds_read_b128 v[168:171], v216 offset:51200
	ds_read_b128 v[172:175], v216 offset:52224
	ds_read_b128 v[192:195], v216 offset:53248
	ds_read_b128 v[196:199], v216 offset:54272
	ds_read_b128 v[200:203], v216 offset:55296
	ds_read_b128 v[218:221], v216 offset:56320
	global_load_lds_dwordx4 v[204:205], off
	s_add_i32 m0, s64, 0x2000
	s_add_u32 s62, s62, 0x80080
	v_lshl_add_u64 v[204:205], v[222:223], 0, s[22:23]
	s_addc_u32 s63, s63, 0
	s_add_i32 s64, s91, s35
	global_load_lds_dwordx4 v[204:205], off
	v_lshl_add_u64 v[204:205], s[62:63], 0, v[178:179]
	s_mov_b32 m0, s64
	s_nop 0
	global_load_lds_dwordx4 v[204:205], off
	v_lshl_add_u64 v[204:205], s[62:63], 0, v[182:183]
	s_add_i32 m0, s64, 0x2000
	s_nop 0
	global_load_lds_dwordx4 v[204:205], off
	v_lshl_add_u64 v[204:205], v[226:227], 0, s[22:23]
	s_mov_b32 m0, s69
	s_nop 0
	global_load_lds_dwordx4 v[204:205], off
	v_lshl_add_u64 v[204:205], v[228:229], 0, s[22:23]
	s_mov_b32 m0, s70
	s_nop 0
	global_load_lds_dwordx4 v[204:205], off
	s_waitcnt vmcnt(8)
	s_waitcnt lgkmcnt(0)
	s_barrier
	s_setprio 1
	s_waitcnt lgkmcnt(0)
	v_mfma_f32_16x16x32_bf16 v[60:63], v[128:131], v[160:163], v[60:63]
	v_mfma_f32_16x16x32_bf16 v[60:63], v[132:135], v[164:167], v[60:63]
	v_mfma_f32_16x16x32_bf16 v[56:59], v[136:139], v[160:163], v[56:59]
	v_mfma_f32_16x16x32_bf16 v[56:59], v[140:143], v[164:167], v[56:59]
	v_mfma_f32_16x16x32_bf16 v[44:47], v[128:131], v[168:171], v[44:47]
	v_mfma_f32_16x16x32_bf16 v[44:47], v[132:135], v[172:175], v[44:47]
	v_mfma_f32_16x16x32_bf16 v[40:43], v[136:139], v[168:171], v[40:43]
	v_mfma_f32_16x16x32_bf16 v[40:43], v[140:143], v[172:175], v[40:43]
	v_mfma_f32_16x16x32_bf16 v[28:31], v[128:131], v[192:195], v[28:31]
	v_mfma_f32_16x16x32_bf16 v[28:31], v[132:135], v[196:199], v[28:31]
	v_mfma_f32_16x16x32_bf16 v[24:27], v[136:139], v[192:195], v[24:27]
	v_mfma_f32_16x16x32_bf16 v[24:27], v[140:143], v[196:199], v[24:27]
	v_mfma_f32_16x16x32_bf16 v[12:15], v[128:131], v[200:203], v[12:15]
	v_mfma_f32_16x16x32_bf16 v[12:15], v[132:135], v[218:221], v[12:15]
	v_mfma_f32_16x16x32_bf16 v[8:11], v[136:139], v[200:203], v[8:11]
	v_mfma_f32_16x16x32_bf16 v[8:11], v[140:143], v[218:221], v[8:11]
	s_setprio 0
	s_setprio 1
	v_mfma_f32_16x16x32_bf16 v[52:55], v[144:147], v[160:163], v[52:55]
	v_mfma_f32_16x16x32_bf16 v[52:55], v[148:151], v[164:167], v[52:55]
	v_mfma_f32_16x16x32_bf16 v[48:51], v[152:155], v[160:163], v[48:51]
	v_mfma_f32_16x16x32_bf16 v[48:51], v[156:159], v[164:167], v[48:51]
	v_mfma_f32_16x16x32_bf16 v[36:39], v[144:147], v[168:171], v[36:39]
	v_mfma_f32_16x16x32_bf16 v[36:39], v[148:151], v[172:175], v[36:39]
	v_mfma_f32_16x16x32_bf16 v[32:35], v[152:155], v[168:171], v[32:35]
	v_mfma_f32_16x16x32_bf16 v[32:35], v[156:159], v[172:175], v[32:35]
	v_mfma_f32_16x16x32_bf16 v[20:23], v[144:147], v[192:195], v[20:23]
	v_mfma_f32_16x16x32_bf16 v[20:23], v[148:151], v[196:199], v[20:23]
	v_mfma_f32_16x16x32_bf16 v[16:19], v[152:155], v[192:195], v[16:19]
	v_mfma_f32_16x16x32_bf16 v[16:19], v[156:159], v[196:199], v[16:19]
	v_mfma_f32_16x16x32_bf16 v[4:7], v[144:147], v[200:203], v[4:7]
	v_mfma_f32_16x16x32_bf16 v[4:7], v[148:151], v[218:221], v[4:7]
	v_mfma_f32_16x16x32_bf16 v[0:3], v[152:155], v[200:203], v[0:3]
	v_mfma_f32_16x16x32_bf16 v[0:3], v[156:159], v[218:221], v[0:3]
	s_setprio 0
	s_barrier
	s_add_u32 s60, s60, 0x100
	s_addc_u32 s61, s61, 0
	s_add_u32 s88, s88, 0x100
	s_addc_u32 s89, s89, 0
	s_cmp_ge_i32 s80, s33
	s_mov_b32 s62, s80
	s_cbranch_scc0 .LBB0_1026
	s_and_b64 vcc, exec, s[24:25]
	s_cbranch_vccz .LBB0_1032

; #define PG8_STAGE(bufoff, gbase, voff) do { _Pragma("unroll") for (int _i = 0; _i < 2; ++_i) \
;         __builtin_amdgcn_global_load_lds((const unsigned*)((const char*)(gbase) + (voff)[_i]), (LAS unsigned*)(lds + (bufoff) + ldsw + _i * 8192), 16, 0, 0); } while (0)
; #define PG8_LDA(dst, b, h) do { _Pragma("unroll") for (int m = 0; m < 4; ++m) _Pragma("unroll") for (int k = 0; k < 2; ++k) dst[m][k] = *(const LAS bf16x8*)(lds + PG8_SA(b, h) + aoff + m * 2048 + k * 1024); } while (0)
; #define PG8_LDB(dst, b, h) do { _Pragma("unroll") for (int n = 0; n < 2; ++n) _Pragma("unroll") for (int k = 0; k < 2; ++k) dst[n][k] = *(const LAS bf16x8*)(lds + PG8_SB(b, h) + boff + n * 2048 + k * 1024); } while (0)
; #define PG8_MMA(ai, bj, At, Bt) do { __builtin_amdgcn_s_setprio(1); _Pragma("unroll") for (int m = 0; m < 4; ++m) _Pragma("unroll") for (int n = 0; n < 2; ++n) _Pragma("unroll") for (int k = 0; k < 2; ++k) \
;         acc[ai][bj][m][n] = __builtin_amdgcn_mfma_f32_16x16x32_bf16(Bt[n][k], At[m][k], acc[ai][bj][m][n], 0, 0, 0); __builtin_amdgcn_s_setprio(0); } while (0)
; #define PG8_WAIT_V(n) asm volatile("s_waitcnt vmcnt(" #n ")" ::: "memory")
; #define PG8_WAIT_L(n) asm volatile("s_waitcnt lgkmcnt(" #n ")" ::: "memory")
; #define PG8_BAR __builtin_amdgcn_s_barrier()
; #define PG8_SCHED __builtin_amdgcn_sched_barrier(0)
; template <int FIXED_NT  , class Epi, class Sched>
; __device__ __forceinline__ void gemm_phase(LAS unsigned char* lds, const int tid_in, const int lda, const int ldb, const Sched& S, const Epi& E) {
;     ...
;         for (int t = 0; t < nt; t += 2) {
;             const bool last = (t == nt - 2);
;             const char* a1 = cA + (size_t)(t + 1) * kstep;
;             const char* a2 = last ? nA : cA + (size_t)(t + 2) * kstep; const char* b2 = last ? nB : cB + (size_t)(t + 2) * kstep;
;             const char* a3 = a2 + kstep; const char* b3 = b2 + kstep;
;             PG8_LDB(B0, 0, 0); PG8_LDB(B1, 0, 1); PG8_SCHED; PG8_LDA(At, 0, 0); PG8_STAGE(PG8_SA(1, 1), a1 + hstepA, voffA);
;             PG8_WAIT_V(8); PG8_WAIT_L(0); PG8_BAR; PG8_MMA(0, 0, At, B0); PG8_MMA(0, 1, At, B1); PG8_BAR; PG8_SCHED;
;             PG8_LDA(At, 0, 1); PG8_STAGE(PG8_SB(0, 0), b2, voffB); PG8_STAGE(PG8_SB(0, 1), b2 + hstepB, voffB); PG8_STAGE(PG8_SA(0, 0), a2, voffA);
.LBB0_1178:
	ds_read_b128 v[154:157], v147
	ds_read_b128 v[158:161], v147 offset:1024
	ds_read_b128 v[162:165], v147 offset:2048
	ds_read_b128 v[166:169], v147 offset:3072
	ds_read_b128 v[170:173], v149
	ds_read_b128 v[174:177], v149 offset:1024
	ds_read_b128 v[178:181], v149 offset:2048
	ds_read_b128 v[182:185], v149 offset:3072
	s_add_i32 s64, s28, 2
	s_add_u32 s29, s24, 0xfff80080
	s_addc_u32 s30, s25, -1
	s_cmp_eq_u32 s59, s28
	s_cselect_b32 s28, s20, s15
	s_cselect_b32 s31, s17, s30
	s_cselect_b32 s30, s16, s29
	s_cselect_b32 s29, s21, s63
	v_lshl_add_u64 v[218:219], s[24:25], 0, v[138:139]
	s_add_i32 m0, s45, 0xc000
	ds_read_b128 v[186:189], v151
	ds_read_b128 v[190:193], v151 offset:1024
	ds_read_b128 v[194:197], v151 offset:2048
	ds_read_b128 v[198:201], v151 offset:3072
	ds_read_b128 v[202:205], v151 offset:4096
	ds_read_b128 v[206:209], v151 offset:5120
	ds_read_b128 v[210:213], v151 offset:6144
	ds_read_b128 v[214:217], v151 offset:7168
	global_load_lds_dwordx4 v[218:219], off
	v_lshl_add_u64 v[218:219], s[24:25], 0, v[140:141]
	s_add_i32 m0, s45, 0xe000
	s_nop 0
	global_load_lds_dwordx4 v[218:219], off
	s_nop 0
	s_waitcnt vmcnt(8)
	s_waitcnt lgkmcnt(0)
	s_barrier
	s_setprio 1
	s_waitcnt lgkmcnt(0)
	v_mfma_f32_16x16x32_bf16 v[124:127], v[154:157], v[186:189], v[124:127]
	v_mfma_f32_16x16x32_bf16 v[124:127], v[158:161], v[190:193], v[124:127]
	v_mfma_f32_16x16x32_bf16 v[120:123], v[162:165], v[186:189], v[120:123]
	v_mfma_f32_16x16x32_bf16 v[120:123], v[166:169], v[190:193], v[120:123]
	v_mfma_f32_16x16x32_bf16 v[108:111], v[154:157], v[194:197], v[108:111]
	v_mfma_f32_16x16x32_bf16 v[108:111], v[158:161], v[198:201], v[108:111]
	v_mfma_f32_16x16x32_bf16 v[104:107], v[162:165], v[194:197], v[104:107]
	v_mfma_f32_16x16x32_bf16 v[104:107], v[166:169], v[198:201], v[104:107]
	v_mfma_f32_16x16x32_bf16 v[92:95], v[154:157], v[202:205], v[92:95]
	v_mfma_f32_16x16x32_bf16 v[92:95], v[158:161], v[206:209], v[92:95]
	v_mfma_f32_16x16x32_bf16 v[88:91], v[162:165], v[202:205], v[88:91]
	v_mfma_f32_16x16x32_bf16 v[88:91], v[166:169], v[206:209], v[88:91]
	v_mfma_f32_16x16x32_bf16 v[76:79], v[154:157], v[210:213], v[76:79]
	v_mfma_f32_16x16x32_bf16 v[76:79], v[158:161], v[214:217], v[76:79]
	v_mfma_f32_16x16x32_bf16 v[72:75], v[162:165], v[210:213], v[72:75]
	v_mfma_f32_16x16x32_bf16 v[72:75], v[166:169], v[214:217], v[72:75]
	s_setprio 0
	s_setprio 1
	v_mfma_f32_16x16x32_bf16 v[116:119], v[170:173], v[186:189], v[116:119]
	v_mfma_f32_16x16x32_bf16 v[116:119], v[174:177], v[190:193], v[116:119]
	v_mfma_f32_16x16x32_bf16 v[112:115], v[178:181], v[186:189], v[112:115]
	v_mfma_f32_16x16x32_bf16 v[112:115], v[182:185], v[190:193], v[112:115]
	v_mfma_f32_16x16x32_bf16 v[100:103], v[170:173], v[194:197], v[100:103]
	v_mfma_f32_16x16x32_bf16 v[100:103], v[174:177], v[198:201], v[100:103]
	v_mfma_f32_16x16x32_bf16 v[96:99], v[178:181], v[194:197], v[96:99]
	v_mfma_f32_16x16x32_bf16 v[96:99], v[182:185], v[198:201], v[96:99]
	v_mfma_f32_16x16x32_bf16 v[84:87], v[170:173], v[202:205], v[84:87]
	v_mfma_f32_16x16x32_bf16 v[84:87], v[174:177], v[206:209], v[84:87]
	v_mfma_f32_16x16x32_bf16 v[80:83], v[178:181], v[202:205], v[80:83]
	v_mfma_f32_16x16x32_bf16 v[80:83], v[182:185], v[206:209], v[80:83]
	v_mfma_f32_16x16x32_bf16 v[68:71], v[170:173], v[210:213], v[68:71]
	v_mfma_f32_16x16x32_bf16 v[68:71], v[174:177], v[214:217], v[68:71]
	v_mfma_f32_16x16x32_bf16 v[64:67], v[178:181], v[210:213], v[64:67]
	v_mfma_f32_16x16x32_bf16 v[64:67], v[182:185], v[214:217], v[64:67]
	s_setprio 0
	s_barrier
	s_add_i32 s65, s60, s35
	v_lshl_add_u64 v[218:219], s[28:29], 0, v[132:133]
	s_mov_b32 m0, s65
	ds_read_b128 v[186:189], v151 offset:16384
	ds_read_b128 v[190:193], v151 offset:17408
	ds_read_b128 v[194:197], v151 offset:18432
	ds_read_b128 v[198:201], v151 offset:19456
	ds_read_b128 v[202:205], v151 offset:20480
	ds_read_b128 v[206:209], v151 offset:21504
	ds_read_b128 v[210:213], v151 offset:22528
	ds_read_b128 v[214:217], v151 offset:23552
	global_load_lds_dwordx4 v[218:219], off
	s_add_i32 m0, s65, 0x2000
	s_add_u32 s66, s28, 0x80000
	v_lshl_add_u64 v[220:221], s[28:29], 0, v[128:129]
	s_addc_u32 s67, s29, 0
	s_add_i32 s65, s61, s35
	global_load_lds_dwordx4 v[220:221], off
	v_lshl_add_u64 v[222:223], s[66:67], 0, v[132:133]
	s_mov_b32 m0, s65
	v_lshl_add_u64 v[226:227], s[30:31], 0, v[130:131]
	global_load_lds_dwordx4 v[222:223], off
	v_lshl_add_u64 v[222:223], s[66:67], 0, v[128:129]
	s_add_i32 m0, s65, 0x2000
	s_nop 0
	global_load_lds_dwordx4 v[222:223], off
	v_lshl_add_u64 v[222:223], s[30:31], 0, v[134:135]
	s_mov_b32 m0, s45
	s_nop 0
	global_load_lds_dwordx4 v[222:223], off
	s_mov_b32 m0, s50
	s_nop 0
	global_load_lds_dwordx4 v[226:227], off
	s_nop 0
	s_waitcnt vmcnt(8)
	s_waitcnt lgkmcnt(0)
	s_barrier
; #define PG8_STAGE(bufoff, gbase, voff) do { _Pragma("unroll") for (int _i = 0; _i < 2; ++_i) \
;         __builtin_amdgcn_global_load_lds((const unsigned*)((const char*)(gbase) + (voff)[_i]), (LAS unsigned*)(lds + (bufoff) + ldsw + _i * 8192), 16, 0, 0); } while (0)
; #define PG8_LDA(dst, b, h) do { _Pragma("unroll") for (int m = 0; m < 4; ++m) _Pragma("unroll") for (int k = 0; k < 2; ++k) dst[m][k] = *(const LAS bf16x8*)(lds + PG8_SA(b, h) + aoff + m * 2048 + k * 1024); } while (0)
; #define PG8_LDB(dst, b, h) do { _Pragma("unroll") for (int n = 0; n < 2; ++n) _Pragma("unroll") for (int k = 0; k < 2; ++k) dst[n][k] = *(const LAS bf16x8*)(lds + PG8_SB(b, h) + boff + n * 2048 + k * 1024); } while (0)
; #define PG8_MMA(ai, bj, At, Bt) do { __builtin_amdgcn_s_setprio(1); _Pragma("unroll") for (int m = 0; m < 4; ++m) _Pragma("unroll") for (int n = 0; n < 2; ++n) _Pragma("unroll") for (int k = 0; k < 2; ++k) \
;         acc[ai][bj][m][n] = __builtin_amdgcn_mfma_f32_16x16x32_bf16(Bt[n][k], At[m][k], acc[ai][bj][m][n], 0, 0, 0); __builtin_amdgcn_s_setprio(0); } while (0)
; #define PG8_WAIT_V(n) asm volatile("s_waitcnt vmcnt(" #n ")" ::: "memory")
; #define PG8_WAIT_L(n) asm volatile("s_waitcnt lgkmcnt(" #n ")" ::: "memory")
; #define PG8_BAR __builtin_amdgcn_s_barrier()
; #define PG8_SCHED __builtin_amdgcn_sched_barrier(0)
; template <int FIXED_NT  , class Epi, class Sched>
; __device__ __forceinline__ void gemm_phase(LAS unsigned char* lds, const int tid_in, const int lda, const int ldb, const Sched& S, const Epi& E) {
;     ...
;             PG8_WAIT_V(8); PG8_WAIT_L(0); PG8_BAR; PG8_MMA(1, 0, At, B0); PG8_MMA(1, 1, At, B1); PG8_BAR; PG8_SCHED;
;             PG8_LDB(B0, 1, 0); PG8_LDB(B1, 1, 1); PG8_SCHED; PG8_LDA(At, 1, 0); PG8_STAGE(PG8_SA(0, 1), a2 + hstepA, voffA);
;             PG8_WAIT_V(8); PG8_WAIT_L(0); PG8_BAR; PG8_MMA(0, 0, At, B0); PG8_MMA(0, 1, At, B1); PG8_BAR; PG8_SCHED;
	s_setprio 1
	s_waitcnt lgkmcnt(0)
	v_mfma_f32_16x16x32_bf16 v[60:63], v[154:157], v[186:189], v[60:63]
	v_mfma_f32_16x16x32_bf16 v[60:63], v[158:161], v[190:193], v[60:63]
	v_mfma_f32_16x16x32_bf16 v[56:59], v[162:165], v[186:189], v[56:59]
	v_mfma_f32_16x16x32_bf16 v[56:59], v[166:169], v[190:193], v[56:59]
	v_mfma_f32_16x16x32_bf16 v[44:47], v[154:157], v[194:197], v[44:47]
	v_mfma_f32_16x16x32_bf16 v[44:47], v[158:161], v[198:201], v[44:47]
	v_mfma_f32_16x16x32_bf16 v[40:43], v[162:165], v[194:197], v[40:43]
	v_mfma_f32_16x16x32_bf16 v[40:43], v[166:169], v[198:201], v[40:43]
	v_mfma_f32_16x16x32_bf16 v[28:31], v[154:157], v[202:205], v[28:31]
	v_mfma_f32_16x16x32_bf16 v[28:31], v[158:161], v[206:209], v[28:31]
	v_mfma_f32_16x16x32_bf16 v[24:27], v[162:165], v[202:205], v[24:27]
	v_mfma_f32_16x16x32_bf16 v[24:27], v[166:169], v[206:209], v[24:27]
	v_mfma_f32_16x16x32_bf16 v[12:15], v[154:157], v[210:213], v[12:15]
	v_mfma_f32_16x16x32_bf16 v[12:15], v[158:161], v[214:217], v[12:15]
	v_mfma_f32_16x16x32_bf16 v[8:11], v[162:165], v[210:213], v[8:11]
	v_mfma_f32_16x16x32_bf16 v[8:11], v[166:169], v[214:217], v[8:11]
	s_setprio 0
	s_setprio 1
	v_mfma_f32_16x16x32_bf16 v[52:55], v[170:173], v[186:189], v[52:55]
	v_mfma_f32_16x16x32_bf16 v[52:55], v[174:177], v[190:193], v[52:55]
	v_mfma_f32_16x16x32_bf16 v[48:51], v[178:181], v[186:189], v[48:51]
	v_mfma_f32_16x16x32_bf16 v[48:51], v[182:185], v[190:193], v[48:51]
	v_mfma_f32_16x16x32_bf16 v[36:39], v[170:173], v[194:197], v[36:39]
	v_mfma_f32_16x16x32_bf16 v[36:39], v[174:177], v[198:201], v[36:39]
	v_mfma_f32_16x16x32_bf16 v[32:35], v[178:181], v[194:197], v[32:35]
	v_mfma_f32_16x16x32_bf16 v[32:35], v[182:185], v[198:201], v[32:35]
	v_mfma_f32_16x16x32_bf16 v[20:23], v[170:173], v[202:205], v[20:23]
	v_mfma_f32_16x16x32_bf16 v[20:23], v[174:177], v[206:209], v[20:23]
	v_mfma_f32_16x16x32_bf16 v[16:19], v[178:181], v[202:205], v[16:19]
	v_mfma_f32_16x16x32_bf16 v[16:19], v[182:185], v[206:209], v[16:19]
	v_mfma_f32_16x16x32_bf16 v[4:7], v[170:173], v[210:213], v[4:7]
	v_mfma_f32_16x16x32_bf16 v[4:7], v[174:177], v[214:217], v[4:7]
	v_mfma_f32_16x16x32_bf16 v[0:3], v[178:181], v[210:213], v[0:3]
	v_mfma_f32_16x16x32_bf16 v[0:3], v[182:185], v[214:217], v[0:3]
	s_setprio 0
	s_barrier
	s_add_i32 s65, 0, 0x18000
	v_add_u32_e32 v142, s65, v145
	s_add_i32 s66, 0, 0x1c000
	ds_read_b128 v[154:157], v142
	ds_read_b128 v[158:161], v142 offset:1024
	ds_read_b128 v[162:165], v142 offset:2048
	ds_read_b128 v[166:169], v142 offset:3072
	v_add_u32_e32 v142, s66, v145
	ds_read_b128 v[170:173], v142
	ds_read_b128 v[174:177], v142 offset:1024
	ds_read_b128 v[178:181], v142 offset:2048
	ds_read_b128 v[182:185], v142 offset:3072
	s_add_u32 s30, s30, 0x80000
	s_addc_u32 s31, s31, 0
	s_mov_b32 m0, s51
	v_lshl_add_u64 v[228:229], s[30:31], 0, v[134:135]
	ds_read_b128 v[186:189], v151 offset:32768
	ds_read_b128 v[190:193], v151 offset:33792
	ds_read_b128 v[194:197], v151 offset:34816
	ds_read_b128 v[198:201], v151 offset:35840
	ds_read_b128 v[202:205], v151 offset:36864
	ds_read_b128 v[206:209], v151 offset:37888
	ds_read_b128 v[210:213], v151 offset:38912
	ds_read_b128 v[214:217], v151 offset:39936
	global_load_lds_dwordx4 v[228:229], off
	v_lshl_add_u64 v[228:229], s[30:31], 0, v[130:131]
	s_mov_b32 m0, s54
	s_nop 0
	global_load_lds_dwordx4 v[228:229], off
	s_nop 0
	s_waitcnt vmcnt(8)
	s_waitcnt lgkmcnt(0)
	s_barrier
	s_setprio 1
	s_waitcnt lgkmcnt(0)
	v_mfma_f32_16x16x32_bf16 v[124:127], v[154:157], v[186:189], v[124:127]
	v_mfma_f32_16x16x32_bf16 v[124:127], v[158:161], v[190:193], v[124:127]
	v_mfma_f32_16x16x32_bf16 v[120:123], v[162:165], v[186:189], v[120:123]
	v_mfma_f32_16x16x32_bf16 v[120:123], v[166:169], v[190:193], v[120:123]
	v_mfma_f32_16x16x32_bf16 v[108:111], v[154:157], v[194:197], v[108:111]
	v_mfma_f32_16x16x32_bf16 v[108:111], v[158:161], v[198:201], v[108:111]
	v_mfma_f32_16x16x32_bf16 v[104:107], v[162:165], v[194:197], v[104:107]
	v_mfma_f32_16x16x32_bf16 v[104:107], v[166:169], v[198:201], v[104:107]
	v_mfma_f32_16x16x32_bf16 v[92:95], v[154:157], v[202:205], v[92:95]
	v_mfma_f32_16x16x32_bf16 v[92:95], v[158:161], v[206:209], v[92:95]
	v_mfma_f32_16x16x32_bf16 v[88:91], v[162:165], v[202:205], v[88:91]
	v_mfma_f32_16x16x32_bf16 v[88:91], v[166:169], v[206:209], v[88:91]
	v_mfma_f32_16x16x32_bf16 v[76:79], v[154:157], v[210:213], v[76:79]
	v_mfma_f32_16x16x32_bf16 v[76:79], v[158:161], v[214:217], v[76:79]
	v_mfma_f32_16x16x32_bf16 v[72:75], v[162:165], v[210:213], v[72:75]
	v_mfma_f32_16x16x32_bf16 v[72:75], v[166:169], v[214:217], v[72:75]
	s_setprio 0
	s_setprio 1
	v_mfma_f32_16x16x32_bf16 v[116:119], v[170:173], v[186:189], v[116:119]
	v_mfma_f32_16x16x32_bf16 v[116:119], v[174:177], v[190:193], v[116:119]
	v_mfma_f32_16x16x32_bf16 v[112:115], v[178:181], v[186:189], v[112:115]
	v_mfma_f32_16x16x32_bf16 v[112:115], v[182:185], v[190:193], v[112:115]
	v_mfma_f32_16x16x32_bf16 v[100:103], v[170:173], v[194:197], v[100:103]
	v_mfma_f32_16x16x32_bf16 v[100:103], v[174:177], v[198:201], v[100:103]
	v_mfma_f32_16x16x32_bf16 v[96:99], v[178:181], v[194:197], v[96:99]
	v_mfma_f32_16x16x32_bf16 v[96:99], v[182:185], v[198:201], v[96:99]
	v_mfma_f32_16x16x32_bf16 v[84:87], v[170:173], v[202:205], v[84:87]
	v_mfma_f32_16x16x32_bf16 v[84:87], v[174:177], v[206:209], v[84:87]
	v_mfma_f32_16x16x32_bf16 v[80:83], v[178:181], v[202:205], v[80:83]
	v_mfma_f32_16x16x32_bf16 v[80:83], v[182:185], v[206:209], v[80:83]
	v_mfma_f32_16x16x32_bf16 v[68:71], v[170:173], v[210:213], v[68:71]
	v_mfma_f32_16x16x32_bf16 v[68:71], v[174:177], v[214:217], v[68:71]
	v_mfma_f32_16x16x32_bf16 v[64:67], v[178:181], v[210:213], v[64:67]
	v_mfma_f32_16x16x32_bf16 v[64:67], v[182:185], v[214:217], v[64:67]
	s_setprio 0
	s_barrier
; #define PG8_STAGE(bufoff, gbase, voff) do { _Pragma("unroll") for (int _i = 0; _i < 2; ++_i) \
;         __builtin_amdgcn_global_load_lds((const unsigned*)((const char*)(gbase) + (voff)[_i]), (LAS unsigned*)(lds + (bufoff) + ldsw + _i * 8192), 16, 0, 0); } while (0)
; #define PG8_LDA(dst, b, h) do { _Pragma("unroll") for (int m = 0; m < 4; ++m) _Pragma("unroll") for (int k = 0; k < 2; ++k) dst[m][k] = *(const LAS bf16x8*)(lds + PG8_SA(b, h) + aoff + m * 2048 + k * 1024); } while (0)
; #define PG8_MMA(ai, bj, At, Bt) do { __builtin_amdgcn_s_setprio(1); _Pragma("unroll") for (int m = 0; m < 4; ++m) _Pragma("unroll") for (int n = 0; n < 2; ++n) _Pragma("unroll") for (int k = 0; k < 2; ++k) \
;         acc[ai][bj][m][n] = __builtin_amdgcn_mfma_f32_16x16x32_bf16(Bt[n][k], At[m][k], acc[ai][bj][m][n], 0, 0, 0); __builtin_amdgcn_s_setprio(0); } while (0)
; #define PG8_WAIT_V(n) asm volatile("s_waitcnt vmcnt(" #n ")" ::: "memory")
; #define PG8_WAIT_L(n) asm volatile("s_waitcnt lgkmcnt(" #n ")" ::: "memory")
; #define PG8_BAR __builtin_amdgcn_s_barrier()
; #define PG8_SCHED __builtin_amdgcn_sched_barrier(0)
; template <int FIXED_NT  , class Epi, class Sched>
; __device__ __forceinline__ void gemm_phase(LAS unsigned char* lds, const int tid_in, const int lda, const int ldb, const Sched& S, const Epi& E) {
;     ...
;             PG8_LDA(At, 1, 1); PG8_STAGE(PG8_SB(1, 0), b3, voffB); PG8_STAGE(PG8_SB(1, 1), b3 + hstepB, voffB); PG8_STAGE(PG8_SA(1, 0), a3, voffA);
;             PG8_WAIT_V(8); PG8_WAIT_L(0); PG8_BAR; PG8_MMA(1, 0, At, B0); PG8_MMA(1, 1, At, B1); PG8_BAR; PG8_SCHED;
;         }
	s_add_i32 s30, s65, s35
	v_lshl_add_u64 v[218:219], v[218:219], 0, s[8:9]
	s_mov_b32 m0, s30
	ds_read_b128 v[186:189], v151 offset:49152
	ds_read_b128 v[190:193], v151 offset:50176
	ds_read_b128 v[194:197], v151 offset:51200
	ds_read_b128 v[198:201], v151 offset:52224
	ds_read_b128 v[202:205], v151 offset:53248
	ds_read_b128 v[206:209], v151 offset:54272
	ds_read_b128 v[210:213], v151 offset:55296
	ds_read_b128 v[214:217], v151 offset:56320
	global_load_lds_dwordx4 v[218:219], off
	s_add_i32 m0, s30, 0x2000
	s_add_u32 s28, s28, 0x80080
	v_lshl_add_u64 v[218:219], v[220:221], 0, s[8:9]
	s_addc_u32 s29, s29, 0
	s_add_i32 s30, s66, s35
	global_load_lds_dwordx4 v[218:219], off
	v_lshl_add_u64 v[218:219], s[28:29], 0, v[132:133]
	s_mov_b32 m0, s30
	s_nop 0
	global_load_lds_dwordx4 v[218:219], off
	v_lshl_add_u64 v[218:219], s[28:29], 0, v[128:129]
	s_add_i32 m0, s30, 0x2000
	s_nop 0
	global_load_lds_dwordx4 v[218:219], off
	v_lshl_add_u64 v[218:219], v[222:223], 0, s[8:9]
	s_mov_b32 m0, s56
	s_nop 0
	global_load_lds_dwordx4 v[218:219], off
	v_lshl_add_u64 v[218:219], v[226:227], 0, s[8:9]
	s_mov_b32 m0, s57
	s_nop 0
	global_load_lds_dwordx4 v[218:219], off
	s_waitcnt vmcnt(8)
	s_waitcnt lgkmcnt(0)
	s_barrier
	s_setprio 1
	s_waitcnt lgkmcnt(0)
	v_mfma_f32_16x16x32_bf16 v[60:63], v[154:157], v[186:189], v[60:63]
	v_mfma_f32_16x16x32_bf16 v[60:63], v[158:161], v[190:193], v[60:63]
	v_mfma_f32_16x16x32_bf16 v[56:59], v[162:165], v[186:189], v[56:59]
	v_mfma_f32_16x16x32_bf16 v[56:59], v[166:169], v[190:193], v[56:59]
	v_mfma_f32_16x16x32_bf16 v[44:47], v[154:157], v[194:197], v[44:47]
	v_mfma_f32_16x16x32_bf16 v[44:47], v[158:161], v[198:201], v[44:47]
	v_mfma_f32_16x16x32_bf16 v[40:43], v[162:165], v[194:197], v[40:43]
	v_mfma_f32_16x16x32_bf16 v[40:43], v[166:169], v[198:201], v[40:43]
	v_mfma_f32_16x16x32_bf16 v[28:31], v[154:157], v[202:205], v[28:31]
	v_mfma_f32_16x16x32_bf16 v[28:31], v[158:161], v[206:209], v[28:31]
	v_mfma_f32_16x16x32_bf16 v[24:27], v[162:165], v[202:205], v[24:27]
	v_mfma_f32_16x16x32_bf16 v[24:27], v[166:169], v[206:209], v[24:27]
	v_mfma_f32_16x16x32_bf16 v[12:15], v[154:157], v[210:213], v[12:15]
	v_mfma_f32_16x16x32_bf16 v[12:15], v[158:161], v[214:217], v[12:15]
	v_mfma_f32_16x16x32_bf16 v[8:11], v[162:165], v[210:213], v[8:11]
	v_mfma_f32_16x16x32_bf16 v[8:11], v[166:169], v[214:217], v[8:11]
	s_setprio 0
	s_setprio 1
	v_mfma_f32_16x16x32_bf16 v[52:55], v[170:173], v[186:189], v[52:55]
	v_mfma_f32_16x16x32_bf16 v[52:55], v[174:177], v[190:193], v[52:55]
	v_mfma_f32_16x16x32_bf16 v[48:51], v[178:181], v[186:189], v[48:51]
	v_mfma_f32_16x16x32_bf16 v[48:51], v[182:185], v[190:193], v[48:51]
	v_mfma_f32_16x16x32_bf16 v[36:39], v[170:173], v[194:197], v[36:39]
	v_mfma_f32_16x16x32_bf16 v[36:39], v[174:177], v[198:201], v[36:39]
	v_mfma_f32_16x16x32_bf16 v[32:35], v[178:181], v[194:197], v[32:35]
	v_mfma_f32_16x16x32_bf16 v[32:35], v[182:185], v[198:201], v[32:35]
	v_mfma_f32_16x16x32_bf16 v[20:23], v[170:173], v[202:205], v[20:23]
	v_mfma_f32_16x16x32_bf16 v[20:23], v[174:177], v[206:209], v[20:23]
	v_mfma_f32_16x16x32_bf16 v[16:19], v[178:181], v[202:205], v[16:19]
	v_mfma_f32_16x16x32_bf16 v[16:19], v[182:185], v[206:209], v[16:19]
	v_mfma_f32_16x16x32_bf16 v[4:7], v[170:173], v[210:213], v[4:7]
	v_mfma_f32_16x16x32_bf16 v[4:7], v[174:177], v[214:217], v[4:7]
	v_mfma_f32_16x16x32_bf16 v[0:3], v[178:181], v[210:213], v[0:3]
	v_mfma_f32_16x16x32_bf16 v[0:3], v[182:185], v[214:217], v[0:3]
	s_setprio 0
	s_barrier
	s_add_u32 s24, s24, 0x100
	s_addc_u32 s25, s25, 0
	s_add_u32 s15, s15, 0x100
	s_addc_u32 s63, s63, 0
	s_cmp_ge_i32 s64, s27
	s_mov_b32 s28, s64
	s_cbranch_scc0 .LBB0_1178
	s_and_b64 vcc, exec, s[12:13]
	s_cbranch_vccz .LBB0_1181

; #define PG8_STAGE(bufoff, gbase, voff) do { _Pragma("unroll") for (int _i = 0; _i < 2; ++_i) \
;         __builtin_amdgcn_global_load_lds((const unsigned*)((const char*)(gbase) + (voff)[_i]), (LAS unsigned*)(lds + (bufoff) + ldsw + _i * 8192), 16, 0, 0); } while (0)
; #define PG8_LDA(dst, b, h) do { _Pragma("unroll") for (int m = 0; m < 4; ++m) _Pragma("unroll") for (int k = 0; k < 2; ++k) dst[m][k] = *(const LAS bf16x8*)(lds + PG8_SA(b, h) + aoff + m * 2048 + k * 1024); } while (0)
; #define PG8_LDB(dst, b, h) do { _Pragma("unroll") for (int n = 0; n < 2; ++n) _Pragma("unroll") for (int k = 0; k < 2; ++k) dst[n][k] = *(const LAS bf16x8*)(lds + PG8_SB(b, h) + boff + n * 2048 + k * 1024); } while (0)
; #define PG8_MMA(ai, bj, At, Bt) do { __builtin_amdgcn_s_setprio(1); _Pragma("unroll") for (int m = 0; m < 4; ++m) _Pragma("unroll") for (int n = 0; n < 2; ++n) _Pragma("unroll") for (int k = 0; k < 2; ++k) \
;         acc[ai][bj][m][n] = __builtin_amdgcn_mfma_f32_16x16x32_bf16(Bt[n][k], At[m][k], acc[ai][bj][m][n], 0, 0, 0); __builtin_amdgcn_s_setprio(0); } while (0)
; #define PG8_WAIT_V(n) asm volatile("s_waitcnt vmcnt(" #n ")" ::: "memory")
; #define PG8_WAIT_L(n) asm volatile("s_waitcnt lgkmcnt(" #n ")" ::: "memory")
; #define PG8_BAR __builtin_amdgcn_s_barrier()
; #define PG8_SCHED __builtin_amdgcn_sched_barrier(0)
; template <int FIXED_NT  , class Epi, class Sched>
; __device__ __forceinline__ void gemm_phase(LAS unsigned char* lds, const int tid_in, const int lda, const int ldb, const Sched& S, const Epi& E) {
;     ...
;         for (int t = 0; t < nt; t += 2) {
;             const bool last = (t == nt - 2);
;             const char* a1 = cA + (size_t)(t + 1) * kstep;
;             const char* a2 = last ? nA : cA + (size_t)(t + 2) * kstep; const char* b2 = last ? nB : cB + (size_t)(t + 2) * kstep;
;             const char* a3 = a2 + kstep; const char* b3 = b2 + kstep;
;             PG8_LDB(B0, 0, 0); PG8_LDB(B1, 0, 1); PG8_SCHED; PG8_LDA(At, 0, 0); PG8_STAGE(PG8_SA(1, 1), a1 + hstepA, voffA);
;             PG8_WAIT_V(8); PG8_WAIT_L(0); PG8_BAR; PG8_MMA(0, 0, At, B0); PG8_MMA(0, 1, At, B1); PG8_BAR; PG8_SCHED;
;             PG8_LDA(At, 0, 1); PG8_STAGE(PG8_SB(0, 0), b2, voffB); PG8_STAGE(PG8_SB(0, 1), b2 + hstepB, voffB); PG8_STAGE(PG8_SA(0, 0), a2, voffA);
.LBB0_1273:
	ds_read_b128 v[128:131], v186
	ds_read_b128 v[132:135], v186 offset:1024
	ds_read_b128 v[136:139], v186 offset:2048
	ds_read_b128 v[140:143], v186 offset:3072
	ds_read_b128 v[144:147], v187
	ds_read_b128 v[148:151], v187 offset:1024
	ds_read_b128 v[152:155], v187 offset:2048
	ds_read_b128 v[170:173], v187 offset:3072
	s_add_i32 s68, s24, 2
	s_add_u32 s22, s4, 0x100
	s_addc_u32 s23, s5, 0
	s_cmp_eq_u32 s65, s24
	s_cselect_b32 s24, s64, s66
	s_cselect_b32 s29, s61, s23
	s_cselect_b32 s28, s62, s22
	s_cselect_b32 s25, s63, s67
	v_lshl_add_u64 v[178:179], s[4:5], 0, v[166:167]
	s_add_i32 m0, s27, 0xc000
	ds_read_b128 v[174:177], v188
	ds_read_b128 v[190:193], v188 offset:1024
	ds_read_b128 v[194:197], v188 offset:2048
	ds_read_b128 v[198:201], v188 offset:3072
	ds_read_b128 v[202:205], v188 offset:4096
	ds_read_b128 v[206:209], v188 offset:5120
	ds_read_b128 v[210:213], v188 offset:6144
	ds_read_b128 v[214:217], v188 offset:7168
	global_load_lds_dwordx4 v[178:179], off
	v_lshl_add_u64 v[178:179], s[4:5], 0, v[168:169]
	s_add_i32 m0, s27, 0xe000
	s_nop 0
	global_load_lds_dwordx4 v[178:179], off
	s_nop 0
	s_waitcnt vmcnt(8)
	s_waitcnt lgkmcnt(0)
	s_barrier
	s_setprio 1
	s_waitcnt lgkmcnt(0)
	v_mfma_f32_16x16x32_bf16 v[124:127], v[128:131], v[174:177], v[124:127]
	v_mfma_f32_16x16x32_bf16 v[124:127], v[132:135], v[190:193], v[124:127]
	v_mfma_f32_16x16x32_bf16 v[120:123], v[136:139], v[174:177], v[120:123]
	v_mfma_f32_16x16x32_bf16 v[120:123], v[140:143], v[190:193], v[120:123]
	v_mfma_f32_16x16x32_bf16 v[108:111], v[128:131], v[194:197], v[108:111]
	v_mfma_f32_16x16x32_bf16 v[108:111], v[132:135], v[198:201], v[108:111]
	v_mfma_f32_16x16x32_bf16 v[104:107], v[136:139], v[194:197], v[104:107]
	v_mfma_f32_16x16x32_bf16 v[104:107], v[140:143], v[198:201], v[104:107]
	v_mfma_f32_16x16x32_bf16 v[92:95], v[128:131], v[202:205], v[92:95]
	v_mfma_f32_16x16x32_bf16 v[92:95], v[132:135], v[206:209], v[92:95]
	v_mfma_f32_16x16x32_bf16 v[88:91], v[136:139], v[202:205], v[88:91]
	v_mfma_f32_16x16x32_bf16 v[88:91], v[140:143], v[206:209], v[88:91]
	v_mfma_f32_16x16x32_bf16 v[76:79], v[128:131], v[210:213], v[76:79]
	v_mfma_f32_16x16x32_bf16 v[76:79], v[132:135], v[214:217], v[76:79]
	v_mfma_f32_16x16x32_bf16 v[72:75], v[136:139], v[210:213], v[72:75]
	v_mfma_f32_16x16x32_bf16 v[72:75], v[140:143], v[214:217], v[72:75]
	s_setprio 0
	s_setprio 1
	v_mfma_f32_16x16x32_bf16 v[116:119], v[144:147], v[174:177], v[116:119]
	v_mfma_f32_16x16x32_bf16 v[116:119], v[148:151], v[190:193], v[116:119]
	v_mfma_f32_16x16x32_bf16 v[112:115], v[152:155], v[174:177], v[112:115]
	v_mfma_f32_16x16x32_bf16 v[112:115], v[170:173], v[190:193], v[112:115]
	v_mfma_f32_16x16x32_bf16 v[100:103], v[144:147], v[194:197], v[100:103]
	v_mfma_f32_16x16x32_bf16 v[100:103], v[148:151], v[198:201], v[100:103]
	v_mfma_f32_16x16x32_bf16 v[96:99], v[152:155], v[194:197], v[96:99]
	v_mfma_f32_16x16x32_bf16 v[96:99], v[170:173], v[198:201], v[96:99]
	v_mfma_f32_16x16x32_bf16 v[84:87], v[144:147], v[202:205], v[84:87]
	v_mfma_f32_16x16x32_bf16 v[84:87], v[148:151], v[206:209], v[84:87]
	v_mfma_f32_16x16x32_bf16 v[80:83], v[152:155], v[202:205], v[80:83]
	v_mfma_f32_16x16x32_bf16 v[80:83], v[170:173], v[206:209], v[80:83]
	v_mfma_f32_16x16x32_bf16 v[68:71], v[144:147], v[210:213], v[68:71]
	v_mfma_f32_16x16x32_bf16 v[68:71], v[148:151], v[214:217], v[68:71]
	v_mfma_f32_16x16x32_bf16 v[64:67], v[152:155], v[210:213], v[64:67]
	v_mfma_f32_16x16x32_bf16 v[64:67], v[170:173], v[214:217], v[64:67]
	s_setprio 0
	s_barrier
	s_add_i32 s4, s50, s3
	v_lshl_add_u64 v[178:179], s[24:25], 0, v[158:159]
	s_mov_b32 m0, s4
	ds_read_b128 v[174:177], v188 offset:16384
	ds_read_b128 v[190:193], v188 offset:17408
	ds_read_b128 v[194:197], v188 offset:18432
	ds_read_b128 v[198:201], v188 offset:19456
	ds_read_b128 v[202:205], v188 offset:20480
	ds_read_b128 v[206:209], v188 offset:21504
	ds_read_b128 v[210:213], v188 offset:22528
	ds_read_b128 v[214:217], v188 offset:23552
	global_load_lds_dwordx4 v[178:179], off
	s_add_i32 m0, s4, 0x2000
	s_add_u32 s4, s24, 0x160000
	v_lshl_add_u64 v[218:219], s[24:25], 0, v[162:163]
	s_addc_u32 s5, s25, 0
	s_add_i32 s69, s51, s3
	global_load_lds_dwordx4 v[218:219], off
	v_lshl_add_u64 v[220:221], s[4:5], 0, v[158:159]
	s_mov_b32 m0, s69
	v_lshl_add_u64 v[222:223], s[28:29], 0, v[160:161]
	global_load_lds_dwordx4 v[220:221], off
	v_lshl_add_u64 v[220:221], s[4:5], 0, v[162:163]
	s_add_i32 m0, s69, 0x2000
	s_nop 0
	global_load_lds_dwordx4 v[220:221], off
	v_lshl_add_u64 v[220:221], s[28:29], 0, v[156:157]
	s_mov_b32 m0, s27
	s_nop 0
	global_load_lds_dwordx4 v[220:221], off
	s_mov_b32 m0, s30
	s_nop 0
	global_load_lds_dwordx4 v[222:223], off
	s_nop 0
	s_waitcnt vmcnt(8)
	s_waitcnt lgkmcnt(0)
	s_barrier
; #define PG8_STAGE(bufoff, gbase, voff) do { _Pragma("unroll") for (int _i = 0; _i < 2; ++_i) \
;         __builtin_amdgcn_global_load_lds((const unsigned*)((const char*)(gbase) + (voff)[_i]), (LAS unsigned*)(lds + (bufoff) + ldsw + _i * 8192), 16, 0, 0); } while (0)
; #define PG8_LDA(dst, b, h) do { _Pragma("unroll") for (int m = 0; m < 4; ++m) _Pragma("unroll") for (int k = 0; k < 2; ++k) dst[m][k] = *(const LAS bf16x8*)(lds + PG8_SA(b, h) + aoff + m * 2048 + k * 1024); } while (0)
; #define PG8_LDB(dst, b, h) do { _Pragma("unroll") for (int n = 0; n < 2; ++n) _Pragma("unroll") for (int k = 0; k < 2; ++k) dst[n][k] = *(const LAS bf16x8*)(lds + PG8_SB(b, h) + boff + n * 2048 + k * 1024); } while (0)
; #define PG8_MMA(ai, bj, At, Bt) do { __builtin_amdgcn_s_setprio(1); _Pragma("unroll") for (int m = 0; m < 4; ++m) _Pragma("unroll") for (int n = 0; n < 2; ++n) _Pragma("unroll") for (int k = 0; k < 2; ++k) \
;         acc[ai][bj][m][n] = __builtin_amdgcn_mfma_f32_16x16x32_bf16(Bt[n][k], At[m][k], acc[ai][bj][m][n], 0, 0, 0); __builtin_amdgcn_s_setprio(0); } while (0)
; #define PG8_WAIT_V(n) asm volatile("s_waitcnt vmcnt(" #n ")" ::: "memory")
; #define PG8_WAIT_L(n) asm volatile("s_waitcnt lgkmcnt(" #n ")" ::: "memory")
; #define PG8_BAR __builtin_amdgcn_s_barrier()
; #define PG8_SCHED __builtin_amdgcn_sched_barrier(0)
; template <int FIXED_NT  , class Epi, class Sched>
; __device__ __forceinline__ void gemm_phase(LAS unsigned char* lds, const int tid_in, const int lda, const int ldb, const Sched& S, const Epi& E) {
;     ...
;             PG8_WAIT_V(8); PG8_WAIT_L(0); PG8_BAR; PG8_MMA(1, 0, At, B0); PG8_MMA(1, 1, At, B1); PG8_BAR; PG8_SCHED;
;             PG8_LDB(B0, 1, 0); PG8_LDB(B1, 1, 1); PG8_SCHED; PG8_LDA(At, 1, 0); PG8_STAGE(PG8_SA(0, 1), a2 + hstepA, voffA);
;             PG8_WAIT_V(8); PG8_WAIT_L(0); PG8_BAR; PG8_MMA(0, 0, At, B0); PG8_MMA(0, 1, At, B1); PG8_BAR; PG8_SCHED;
	s_setprio 1
	s_waitcnt lgkmcnt(0)
	v_mfma_f32_16x16x32_bf16 v[60:63], v[128:131], v[174:177], v[60:63]
	v_mfma_f32_16x16x32_bf16 v[60:63], v[132:135], v[190:193], v[60:63]
	v_mfma_f32_16x16x32_bf16 v[56:59], v[136:139], v[174:177], v[56:59]
	v_mfma_f32_16x16x32_bf16 v[56:59], v[140:143], v[190:193], v[56:59]
	v_mfma_f32_16x16x32_bf16 v[44:47], v[128:131], v[194:197], v[44:47]
	v_mfma_f32_16x16x32_bf16 v[44:47], v[132:135], v[198:201], v[44:47]
	v_mfma_f32_16x16x32_bf16 v[40:43], v[136:139], v[194:197], v[40:43]
	v_mfma_f32_16x16x32_bf16 v[40:43], v[140:143], v[198:201], v[40:43]
	v_mfma_f32_16x16x32_bf16 v[28:31], v[128:131], v[202:205], v[28:31]
	v_mfma_f32_16x16x32_bf16 v[28:31], v[132:135], v[206:209], v[28:31]
	v_mfma_f32_16x16x32_bf16 v[24:27], v[136:139], v[202:205], v[24:27]
	v_mfma_f32_16x16x32_bf16 v[24:27], v[140:143], v[206:209], v[24:27]
	v_mfma_f32_16x16x32_bf16 v[12:15], v[128:131], v[210:213], v[12:15]
	v_mfma_f32_16x16x32_bf16 v[12:15], v[132:135], v[214:217], v[12:15]
	v_mfma_f32_16x16x32_bf16 v[8:11], v[136:139], v[210:213], v[8:11]
	v_mfma_f32_16x16x32_bf16 v[8:11], v[140:143], v[214:217], v[8:11]
	s_setprio 0
	s_setprio 1
	v_mfma_f32_16x16x32_bf16 v[52:55], v[144:147], v[174:177], v[52:55]
	v_mfma_f32_16x16x32_bf16 v[52:55], v[148:151], v[190:193], v[52:55]
	v_mfma_f32_16x16x32_bf16 v[48:51], v[152:155], v[174:177], v[48:51]
	v_mfma_f32_16x16x32_bf16 v[48:51], v[170:173], v[190:193], v[48:51]
	v_mfma_f32_16x16x32_bf16 v[36:39], v[144:147], v[194:197], v[36:39]
	v_mfma_f32_16x16x32_bf16 v[36:39], v[148:151], v[198:201], v[36:39]
	v_mfma_f32_16x16x32_bf16 v[32:35], v[152:155], v[194:197], v[32:35]
	v_mfma_f32_16x16x32_bf16 v[32:35], v[170:173], v[198:201], v[32:35]
	v_mfma_f32_16x16x32_bf16 v[20:23], v[144:147], v[202:205], v[20:23]
	v_mfma_f32_16x16x32_bf16 v[20:23], v[148:151], v[206:209], v[20:23]
	v_mfma_f32_16x16x32_bf16 v[16:19], v[152:155], v[202:205], v[16:19]
	v_mfma_f32_16x16x32_bf16 v[16:19], v[170:173], v[206:209], v[16:19]
	v_mfma_f32_16x16x32_bf16 v[4:7], v[144:147], v[210:213], v[4:7]
	v_mfma_f32_16x16x32_bf16 v[4:7], v[148:151], v[214:217], v[4:7]
	v_mfma_f32_16x16x32_bf16 v[0:3], v[152:155], v[210:213], v[0:3]
	v_mfma_f32_16x16x32_bf16 v[0:3], v[170:173], v[214:217], v[0:3]
	s_setprio 0
	s_barrier
	s_add_i32 s69, 0, 0x18000
	s_add_i32 s70, 0, 0x1c000
	v_add_u32_e32 v140, s69, v181
	v_add_u32_e32 v170, s70, v181
	ds_read_b128 v[128:131], v140
	ds_read_b128 v[132:135], v140 offset:1024
	ds_read_b128 v[136:139], v140 offset:2048
	ds_read_b128 v[140:143], v140 offset:3072
	ds_read_b128 v[144:147], v170
	ds_read_b128 v[148:151], v170 offset:1024
	ds_read_b128 v[152:155], v170 offset:2048
	ds_read_b128 v[170:173], v170 offset:3072
	s_add_u32 s4, s28, 0x160000
	s_addc_u32 s5, s29, 0
	s_mov_b32 m0, s31
	v_lshl_add_u64 v[226:227], s[4:5], 0, v[156:157]
	ds_read_b128 v[174:177], v188 offset:32768
	ds_read_b128 v[190:193], v188 offset:33792
	ds_read_b128 v[194:197], v188 offset:34816
	ds_read_b128 v[198:201], v188 offset:35840
	ds_read_b128 v[202:205], v188 offset:36864
	ds_read_b128 v[206:209], v188 offset:37888
	ds_read_b128 v[210:213], v188 offset:38912
	ds_read_b128 v[214:217], v188 offset:39936
	global_load_lds_dwordx4 v[226:227], off
	v_lshl_add_u64 v[226:227], s[4:5], 0, v[160:161]
	s_mov_b32 m0, s35
	s_nop 0
	global_load_lds_dwordx4 v[226:227], off
	s_nop 0
	s_waitcnt vmcnt(8)
	s_waitcnt lgkmcnt(0)
	s_barrier
	s_setprio 1
	s_waitcnt lgkmcnt(0)
	v_mfma_f32_16x16x32_bf16 v[124:127], v[128:131], v[174:177], v[124:127]
	v_mfma_f32_16x16x32_bf16 v[124:127], v[132:135], v[190:193], v[124:127]
	v_mfma_f32_16x16x32_bf16 v[120:123], v[136:139], v[174:177], v[120:123]
	v_mfma_f32_16x16x32_bf16 v[120:123], v[140:143], v[190:193], v[120:123]
	v_mfma_f32_16x16x32_bf16 v[108:111], v[128:131], v[194:197], v[108:111]
	v_mfma_f32_16x16x32_bf16 v[108:111], v[132:135], v[198:201], v[108:111]
	v_mfma_f32_16x16x32_bf16 v[104:107], v[136:139], v[194:197], v[104:107]
	v_mfma_f32_16x16x32_bf16 v[104:107], v[140:143], v[198:201], v[104:107]
	v_mfma_f32_16x16x32_bf16 v[92:95], v[128:131], v[202:205], v[92:95]
	v_mfma_f32_16x16x32_bf16 v[92:95], v[132:135], v[206:209], v[92:95]
	v_mfma_f32_16x16x32_bf16 v[88:91], v[136:139], v[202:205], v[88:91]
	v_mfma_f32_16x16x32_bf16 v[88:91], v[140:143], v[206:209], v[88:91]
	v_mfma_f32_16x16x32_bf16 v[76:79], v[128:131], v[210:213], v[76:79]
	v_mfma_f32_16x16x32_bf16 v[76:79], v[132:135], v[214:217], v[76:79]
	v_mfma_f32_16x16x32_bf16 v[72:75], v[136:139], v[210:213], v[72:75]
	v_mfma_f32_16x16x32_bf16 v[72:75], v[140:143], v[214:217], v[72:75]
	s_setprio 0
	s_setprio 1
	v_mfma_f32_16x16x32_bf16 v[116:119], v[144:147], v[174:177], v[116:119]
	v_mfma_f32_16x16x32_bf16 v[116:119], v[148:151], v[190:193], v[116:119]
	v_mfma_f32_16x16x32_bf16 v[112:115], v[152:155], v[174:177], v[112:115]
	v_mfma_f32_16x16x32_bf16 v[112:115], v[170:173], v[190:193], v[112:115]
	v_mfma_f32_16x16x32_bf16 v[100:103], v[144:147], v[194:197], v[100:103]
	v_mfma_f32_16x16x32_bf16 v[100:103], v[148:151], v[198:201], v[100:103]
	v_mfma_f32_16x16x32_bf16 v[96:99], v[152:155], v[194:197], v[96:99]
	v_mfma_f32_16x16x32_bf16 v[96:99], v[170:173], v[198:201], v[96:99]
	v_mfma_f32_16x16x32_bf16 v[84:87], v[144:147], v[202:205], v[84:87]
	v_mfma_f32_16x16x32_bf16 v[84:87], v[148:151], v[206:209], v[84:87]
	v_mfma_f32_16x16x32_bf16 v[80:83], v[152:155], v[202:205], v[80:83]
	v_mfma_f32_16x16x32_bf16 v[80:83], v[170:173], v[206:209], v[80:83]
	v_mfma_f32_16x16x32_bf16 v[68:71], v[144:147], v[210:213], v[68:71]
	v_mfma_f32_16x16x32_bf16 v[68:71], v[148:151], v[214:217], v[68:71]
	v_mfma_f32_16x16x32_bf16 v[64:67], v[152:155], v[210:213], v[64:67]
	v_mfma_f32_16x16x32_bf16 v[64:67], v[170:173], v[214:217], v[64:67]
	s_setprio 0
	s_barrier
; #define PG8_STAGE(bufoff, gbase, voff) do { _Pragma("unroll") for (int _i = 0; _i < 2; ++_i) \
;         __builtin_amdgcn_global_load_lds((const unsigned*)((const char*)(gbase) + (voff)[_i]), (LAS unsigned*)(lds + (bufoff) + ldsw + _i * 8192), 16, 0, 0); } while (0)
; #define PG8_LDA(dst, b, h) do { _Pragma("unroll") for (int m = 0; m < 4; ++m) _Pragma("unroll") for (int k = 0; k < 2; ++k) dst[m][k] = *(const LAS bf16x8*)(lds + PG8_SA(b, h) + aoff + m * 2048 + k * 1024); } while (0)
; #define PG8_MMA(ai, bj, At, Bt) do { __builtin_amdgcn_s_setprio(1); _Pragma("unroll") for (int m = 0; m < 4; ++m) _Pragma("unroll") for (int n = 0; n < 2; ++n) _Pragma("unroll") for (int k = 0; k < 2; ++k) \
;         acc[ai][bj][m][n] = __builtin_amdgcn_mfma_f32_16x16x32_bf16(Bt[n][k], At[m][k], acc[ai][bj][m][n], 0, 0, 0); __builtin_amdgcn_s_setprio(0); } while (0)
; #define PG8_WAIT_V(n) asm volatile("s_waitcnt vmcnt(" #n ")" ::: "memory")
; #define PG8_WAIT_L(n) asm volatile("s_waitcnt lgkmcnt(" #n ")" ::: "memory")
; #define PG8_BAR __builtin_amdgcn_s_barrier()
; #define PG8_SCHED __builtin_amdgcn_sched_barrier(0)
; template <int FIXED_NT  , class Epi, class Sched>
; __device__ __forceinline__ void gemm_phase(LAS unsigned char* lds, const int tid_in, const int lda, const int ldb, const Sched& S, const Epi& E) {
;     ...
;             PG8_LDA(At, 1, 1); PG8_STAGE(PG8_SB(1, 0), b3, voffB); PG8_STAGE(PG8_SB(1, 1), b3 + hstepB, voffB); PG8_STAGE(PG8_SA(1, 0), a3, voffA);
;             PG8_WAIT_V(8); PG8_WAIT_L(0); PG8_BAR; PG8_MMA(1, 0, At, B0); PG8_MMA(1, 1, At, B1); PG8_BAR; PG8_SCHED;
;         }
	s_add_i32 s4, s69, s3
	v_lshl_add_u64 v[178:179], v[178:179], 0, s[10:11]
	s_mov_b32 m0, s4
	ds_read_b128 v[174:177], v188 offset:49152
	ds_read_b128 v[190:193], v188 offset:50176
	ds_read_b128 v[194:197], v188 offset:51200
	ds_read_b128 v[198:201], v188 offset:52224
	ds_read_b128 v[202:205], v188 offset:53248
	ds_read_b128 v[206:209], v188 offset:54272
	ds_read_b128 v[210:213], v188 offset:55296
	ds_read_b128 v[214:217], v188 offset:56320
	global_load_lds_dwordx4 v[178:179], off
	s_add_i32 m0, s4, 0x2000
	s_add_u32 s4, s24, 0x160080
	v_lshl_add_u64 v[178:179], v[218:219], 0, s[10:11]
	s_addc_u32 s5, s25, 0
	s_add_i32 s24, s70, s3
	global_load_lds_dwordx4 v[178:179], off
	v_lshl_add_u64 v[178:179], s[4:5], 0, v[158:159]
	s_mov_b32 m0, s24
	s_nop 0
	global_load_lds_dwordx4 v[178:179], off
	v_lshl_add_u64 v[178:179], s[4:5], 0, v[162:163]
	s_add_i32 m0, s24, 0x2000
	s_nop 0
	global_load_lds_dwordx4 v[178:179], off
	v_lshl_add_u64 v[178:179], v[220:221], 0, s[10:11]
	s_mov_b32 m0, s44
	s_nop 0
	global_load_lds_dwordx4 v[178:179], off
	v_lshl_add_u64 v[178:179], v[222:223], 0, s[10:11]
	s_mov_b32 m0, s45
	s_nop 0
	global_load_lds_dwordx4 v[178:179], off
	s_waitcnt vmcnt(8)
	s_waitcnt lgkmcnt(0)
	s_barrier
	s_setprio 1
	s_waitcnt lgkmcnt(0)
	v_mfma_f32_16x16x32_bf16 v[60:63], v[128:131], v[174:177], v[60:63]
	v_mfma_f32_16x16x32_bf16 v[60:63], v[132:135], v[190:193], v[60:63]
	v_mfma_f32_16x16x32_bf16 v[56:59], v[136:139], v[174:177], v[56:59]
	v_mfma_f32_16x16x32_bf16 v[56:59], v[140:143], v[190:193], v[56:59]
	v_mfma_f32_16x16x32_bf16 v[44:47], v[128:131], v[194:197], v[44:47]
	v_mfma_f32_16x16x32_bf16 v[44:47], v[132:135], v[198:201], v[44:47]
	v_mfma_f32_16x16x32_bf16 v[40:43], v[136:139], v[194:197], v[40:43]
	v_mfma_f32_16x16x32_bf16 v[40:43], v[140:143], v[198:201], v[40:43]
	v_mfma_f32_16x16x32_bf16 v[28:31], v[128:131], v[202:205], v[28:31]
	v_mfma_f32_16x16x32_bf16 v[28:31], v[132:135], v[206:209], v[28:31]
	v_mfma_f32_16x16x32_bf16 v[24:27], v[136:139], v[202:205], v[24:27]
	v_mfma_f32_16x16x32_bf16 v[24:27], v[140:143], v[206:209], v[24:27]
	v_mfma_f32_16x16x32_bf16 v[12:15], v[128:131], v[210:213], v[12:15]
	v_mfma_f32_16x16x32_bf16 v[12:15], v[132:135], v[214:217], v[12:15]
	v_mfma_f32_16x16x32_bf16 v[8:11], v[136:139], v[210:213], v[8:11]
	v_mfma_f32_16x16x32_bf16 v[8:11], v[140:143], v[214:217], v[8:11]
	s_setprio 0
	s_setprio 1
	v_mfma_f32_16x16x32_bf16 v[52:55], v[144:147], v[174:177], v[52:55]
	v_mfma_f32_16x16x32_bf16 v[52:55], v[148:151], v[190:193], v[52:55]
	v_mfma_f32_16x16x32_bf16 v[48:51], v[152:155], v[174:177], v[48:51]
	v_mfma_f32_16x16x32_bf16 v[48:51], v[170:173], v[190:193], v[48:51]
	v_mfma_f32_16x16x32_bf16 v[36:39], v[144:147], v[194:197], v[36:39]
	v_mfma_f32_16x16x32_bf16 v[36:39], v[148:151], v[198:201], v[36:39]
	v_mfma_f32_16x16x32_bf16 v[32:35], v[152:155], v[194:197], v[32:35]
	v_mfma_f32_16x16x32_bf16 v[32:35], v[170:173], v[198:201], v[32:35]
	v_mfma_f32_16x16x32_bf16 v[20:23], v[144:147], v[202:205], v[20:23]
	v_mfma_f32_16x16x32_bf16 v[20:23], v[148:151], v[206:209], v[20:23]
	v_mfma_f32_16x16x32_bf16 v[16:19], v[152:155], v[202:205], v[16:19]
	v_mfma_f32_16x16x32_bf16 v[16:19], v[170:173], v[206:209], v[16:19]
	v_mfma_f32_16x16x32_bf16 v[4:7], v[144:147], v[210:213], v[4:7]
	v_mfma_f32_16x16x32_bf16 v[4:7], v[148:151], v[214:217], v[4:7]
	v_mfma_f32_16x16x32_bf16 v[0:3], v[152:155], v[210:213], v[0:3]
	v_mfma_f32_16x16x32_bf16 v[0:3], v[170:173], v[214:217], v[0:3]
	s_setprio 0
	s_barrier
	s_add_u32 s66, s66, 0x100
	s_addc_u32 s67, s67, 0
	s_cmp_ge_i32 s68, s60
	s_mov_b64 s[4:5], s[22:23]
	s_mov_b32 s24, s68
	s_cbranch_scc0 .LBB0_1273
	s_and_b64 vcc, exec, s[12:13]
	s_cbranch_vccz .LBB0_1276
